# parameter variant: GEMM barrier behind the first 6 MFMAs after the short load phase and the first 2 after the long one
# baseline (speedup 1.0000x reference)
.LBB0_168:
	s_add_u32 s46, s66, 0xfff80080
	s_addc_u32 s47, s67, -1
	s_add_i32 s62, 0, 0x10000
	s_cmp_eq_u32 s82, 28
	s_cselect_b32 s69, s17, s47
	s_cselect_b32 s68, s65, s46
	v_add_u32_e32 v143, s62, v140
	s_cselect_b32 s61, s13, s81
	s_cselect_b32 s60, s79, s80
	s_add_i32 s63, 0, 0x14000
	ds_read_b128 v[144:147], v143
	ds_read_b128 v[148:151], v143 offset:1024
	ds_read_b128 v[152:155], v143 offset:2048
	ds_read_b128 v[156:159], v143 offset:3072
	v_add_u32_e32 v143, s63, v140
	ds_read_b128 v[160:163], v143
	ds_read_b128 v[178:181], v143 offset:1024
	ds_read_b128 v[182:185], v143 offset:2048
	ds_read_b128 v[186:189], v143 offset:3072
	v_lshl_add_u64 v[164:165], s[66:67], 0, v[136:137]
	s_add_i32 m0, s19, 0xc000
	ds_read_b128 v[206:209], v142
	ds_read_b128 v[210:213], v142 offset:1024
	ds_read_b128 v[214:217], v142 offset:2048
	ds_read_b128 v[218:221], v142 offset:3072
	ds_read_b128 v[222:225], v142 offset:4096
	ds_read_b128 v[226:229], v142 offset:5120
	ds_read_b128 v[230:233], v142 offset:6144
	ds_read_b128 v[234:237], v142 offset:7168
	global_load_lds_dwordx4 v[164:165], off
	v_lshl_add_u64 v[164:165], s[66:67], 0, v[138:139]
	s_add_i32 m0, s19, 0xe000
	s_nop 0
	global_load_lds_dwordx4 v[164:165], off
	s_waitcnt vmcnt(8)
	s_waitcnt lgkmcnt(0)
	s_setprio 1
	s_waitcnt lgkmcnt(0)
	v_mfma_f32_16x16x32_bf16 v[126:129], v[144:147], v[206:209], v[126:129]
	v_mfma_f32_16x16x32_bf16 v[122:125], v[152:155], v[206:209], v[122:125]
	v_mfma_f32_16x16x32_bf16 v[118:121], v[144:147], v[214:217], v[118:121]
	v_mfma_f32_16x16x32_bf16 v[114:117], v[152:155], v[214:217], v[114:117]
	v_mfma_f32_16x16x32_bf16 v[102:105], v[144:147], v[222:225], v[102:105]
	v_mfma_f32_16x16x32_bf16 v[98:101], v[152:155], v[222:225], v[98:101]
	s_barrier
	v_mfma_f32_16x16x32_bf16 v[86:89], v[144:147], v[230:233], v[86:89]
	v_mfma_f32_16x16x32_bf16 v[82:85], v[152:155], v[230:233], v[82:85]
	v_mfma_f32_16x16x32_bf16 v[126:129], v[148:151], v[210:213], v[126:129]
	v_mfma_f32_16x16x32_bf16 v[122:125], v[156:159], v[210:213], v[122:125]
	v_mfma_f32_16x16x32_bf16 v[118:121], v[148:151], v[218:221], v[118:121]
	v_mfma_f32_16x16x32_bf16 v[114:117], v[156:159], v[218:221], v[114:117]
	v_mfma_f32_16x16x32_bf16 v[102:105], v[148:151], v[226:229], v[102:105]
	v_mfma_f32_16x16x32_bf16 v[98:101], v[156:159], v[226:229], v[98:101]
	v_mfma_f32_16x16x32_bf16 v[86:89], v[148:151], v[234:237], v[86:89]
	v_mfma_f32_16x16x32_bf16 v[82:85], v[156:159], v[234:237], v[82:85]
	v_mfma_f32_16x16x32_bf16 v[110:113], v[160:163], v[206:209], v[110:113]
	v_mfma_f32_16x16x32_bf16 v[106:109], v[182:185], v[206:209], v[106:109]
	v_mfma_f32_16x16x32_bf16 v[94:97], v[160:163], v[214:217], v[94:97]
	v_mfma_f32_16x16x32_bf16 v[90:93], v[182:185], v[214:217], v[90:93]
	v_mfma_f32_16x16x32_bf16 v[78:81], v[160:163], v[222:225], v[78:81]
	v_mfma_f32_16x16x32_bf16 v[74:77], v[182:185], v[222:225], v[74:77]
	v_mfma_f32_16x16x32_bf16 v[70:73], v[160:163], v[230:233], v[70:73]
	v_mfma_f32_16x16x32_bf16 v[66:69], v[182:185], v[230:233], v[66:69]
	v_mfma_f32_16x16x32_bf16 v[110:113], v[178:181], v[210:213], v[110:113]
	v_mfma_f32_16x16x32_bf16 v[106:109], v[186:189], v[210:213], v[106:109]
	v_mfma_f32_16x16x32_bf16 v[94:97], v[178:181], v[218:221], v[94:97]
	v_mfma_f32_16x16x32_bf16 v[90:93], v[186:189], v[218:221], v[90:93]
	v_mfma_f32_16x16x32_bf16 v[78:81], v[178:181], v[226:229], v[78:81]
	v_mfma_f32_16x16x32_bf16 v[74:77], v[186:189], v[226:229], v[74:77]
	v_mfma_f32_16x16x32_bf16 v[70:73], v[178:181], v[234:237], v[70:73]
	v_mfma_f32_16x16x32_bf16 v[66:69], v[186:189], v[234:237], v[66:69]
	s_barrier
	s_setprio 0
	s_add_i32 s46, s62, s71
	v_lshl_add_u64 v[164:165], s[60:61], 0, v[166:167]
	s_mov_b32 m0, s46
	ds_read_b128 v[206:209], v142 offset:16384
	ds_read_b128 v[210:213], v142 offset:17408
	ds_read_b128 v[214:217], v142 offset:18432
	ds_read_b128 v[218:221], v142 offset:19456
	ds_read_b128 v[222:225], v142 offset:20480
	ds_read_b128 v[226:229], v142 offset:21504
	ds_read_b128 v[230:233], v142 offset:22528
	ds_read_b128 v[234:237], v142 offset:23552
	global_load_lds_dwordx4 v[164:165], off
	s_add_i32 m0, s46, 0x2000
	s_add_u32 s46, s60, 0x80000
	v_lshl_add_u64 v[242:243], s[60:61], 0, v[130:131]
	s_addc_u32 s47, s61, 0
	s_add_i32 s62, s63, s71
	global_load_lds_dwordx4 v[242:243], off
	v_lshl_add_u64 v[244:245], s[46:47], 0, v[166:167]
	s_mov_b32 m0, s62
	v_lshl_add_u64 v[246:247], s[68:69], 0, v[132:133]
	global_load_lds_dwordx4 v[244:245], off
	v_lshl_add_u64 v[244:245], s[46:47], 0, v[130:131]
	s_add_i32 m0, s62, 0x2000
	s_nop 0
	global_load_lds_dwordx4 v[244:245], off
	v_lshl_add_u64 v[244:245], s[68:69], 0, v[134:135]
	s_mov_b32 m0, s19
	s_nop 0
	global_load_lds_dwordx4 v[244:245], off
	s_mov_b32 m0, s73
	s_nop 0
	global_load_lds_dwordx4 v[246:247], off
	s_waitcnt vmcnt(8)
	s_waitcnt lgkmcnt(0)
	s_setprio 1
	s_waitcnt lgkmcnt(0)
	v_mfma_f32_16x16x32_bf16 v[62:65], v[144:147], v[206:209], v[62:65]
	v_mfma_f32_16x16x32_bf16 v[58:61], v[152:155], v[206:209], v[58:61]
	s_barrier
	v_mfma_f32_16x16x32_bf16 v[54:57], v[144:147], v[214:217], v[54:57]
	v_mfma_f32_16x16x32_bf16 v[50:53], v[152:155], v[214:217], v[50:53]
	v_mfma_f32_16x16x32_bf16 v[38:41], v[144:147], v[222:225], v[38:41]
	v_mfma_f32_16x16x32_bf16 v[34:37], v[152:155], v[222:225], v[34:37]
	v_mfma_f32_16x16x32_bf16 v[22:25], v[144:147], v[230:233], v[22:25]
	v_mfma_f32_16x16x32_bf16 v[18:21], v[152:155], v[230:233], v[18:21]
	v_mfma_f32_16x16x32_bf16 v[62:65], v[148:151], v[210:213], v[62:65]
	v_mfma_f32_16x16x32_bf16 v[58:61], v[156:159], v[210:213], v[58:61]
	v_mfma_f32_16x16x32_bf16 v[54:57], v[148:151], v[218:221], v[54:57]
	v_mfma_f32_16x16x32_bf16 v[50:53], v[156:159], v[218:221], v[50:53]
	v_mfma_f32_16x16x32_bf16 v[38:41], v[148:151], v[226:229], v[38:41]
	v_mfma_f32_16x16x32_bf16 v[34:37], v[156:159], v[226:229], v[34:37]
	v_mfma_f32_16x16x32_bf16 v[22:25], v[148:151], v[234:237], v[22:25]
	v_mfma_f32_16x16x32_bf16 v[18:21], v[156:159], v[234:237], v[18:21]
	v_mfma_f32_16x16x32_bf16 v[46:49], v[160:163], v[206:209], v[46:49]
	v_mfma_f32_16x16x32_bf16 v[42:45], v[182:185], v[206:209], v[42:45]
	v_mfma_f32_16x16x32_bf16 v[30:33], v[160:163], v[214:217], v[30:33]
	v_mfma_f32_16x16x32_bf16 v[26:29], v[182:185], v[214:217], v[26:29]
	v_mfma_f32_16x16x32_bf16 v[14:17], v[160:163], v[222:225], v[14:17]
	v_mfma_f32_16x16x32_bf16 v[10:13], v[182:185], v[222:225], v[10:13]
	v_mfma_f32_16x16x32_bf16 v[6:9], v[160:163], v[230:233], v[6:9]
	v_mfma_f32_16x16x32_bf16 v[2:5], v[182:185], v[230:233], v[2:5]
	v_mfma_f32_16x16x32_bf16 v[46:49], v[178:181], v[210:213], v[46:49]
	v_mfma_f32_16x16x32_bf16 v[42:45], v[186:189], v[210:213], v[42:45]
	v_mfma_f32_16x16x32_bf16 v[30:33], v[178:181], v[218:221], v[30:33]
	v_mfma_f32_16x16x32_bf16 v[26:29], v[186:189], v[218:221], v[26:29]
	v_mfma_f32_16x16x32_bf16 v[14:17], v[178:181], v[226:229], v[14:17]
	v_mfma_f32_16x16x32_bf16 v[10:13], v[186:189], v[226:229], v[10:13]
	v_mfma_f32_16x16x32_bf16 v[6:9], v[178:181], v[234:237], v[6:9]
	v_mfma_f32_16x16x32_bf16 v[2:5], v[186:189], v[234:237], v[2:5]
	s_barrier
	s_setprio 0
	s_add_i32 s62, 0, 0x18000
	v_add_u32_e32 v143, s62, v140
	s_add_i32 s63, 0, 0x1c000
	ds_read_b128 v[144:147], v143
	ds_read_b128 v[148:151], v143 offset:1024
	ds_read_b128 v[152:155], v143 offset:2048
	ds_read_b128 v[156:159], v143 offset:3072
	v_add_u32_e32 v143, s63, v140
	ds_read_b128 v[160:163], v143
	ds_read_b128 v[178:181], v143 offset:1024
	ds_read_b128 v[182:185], v143 offset:2048
	ds_read_b128 v[186:189], v143 offset:3072
	s_add_u32 s46, s68, 0x80000
	s_addc_u32 s47, s69, 0
	s_mov_b32 m0, s74
	v_lshl_add_u64 v[248:249], s[46:47], 0, v[134:135]
	ds_read_b128 v[206:209], v142 offset:32768
	ds_read_b128 v[210:213], v142 offset:33792
	ds_read_b128 v[214:217], v142 offset:34816
	ds_read_b128 v[218:221], v142 offset:35840
	ds_read_b128 v[222:225], v142 offset:36864
	ds_read_b128 v[226:229], v142 offset:37888
	ds_read_b128 v[230:233], v142 offset:38912
	ds_read_b128 v[234:237], v142 offset:39936
	global_load_lds_dwordx4 v[248:249], off
	v_lshl_add_u64 v[248:249], s[46:47], 0, v[132:133]
	s_mov_b32 m0, s75
	s_nop 0
	global_load_lds_dwordx4 v[248:249], off
	s_waitcnt vmcnt(8)
	s_waitcnt lgkmcnt(0)
	s_setprio 1
	s_waitcnt lgkmcnt(0)
	v_mfma_f32_16x16x32_bf16 v[126:129], v[144:147], v[206:209], v[126:129]
	v_mfma_f32_16x16x32_bf16 v[122:125], v[152:155], v[206:209], v[122:125]
	v_mfma_f32_16x16x32_bf16 v[118:121], v[144:147], v[214:217], v[118:121]
	v_mfma_f32_16x16x32_bf16 v[114:117], v[152:155], v[214:217], v[114:117]
	v_mfma_f32_16x16x32_bf16 v[102:105], v[144:147], v[222:225], v[102:105]
	v_mfma_f32_16x16x32_bf16 v[98:101], v[152:155], v[222:225], v[98:101]
	s_barrier
	v_mfma_f32_16x16x32_bf16 v[86:89], v[144:147], v[230:233], v[86:89]
	v_mfma_f32_16x16x32_bf16 v[82:85], v[152:155], v[230:233], v[82:85]
	v_mfma_f32_16x16x32_bf16 v[126:129], v[148:151], v[210:213], v[126:129]
	v_mfma_f32_16x16x32_bf16 v[122:125], v[156:159], v[210:213], v[122:125]
	v_mfma_f32_16x16x32_bf16 v[118:121], v[148:151], v[218:221], v[118:121]
	v_mfma_f32_16x16x32_bf16 v[114:117], v[156:159], v[218:221], v[114:117]
	v_mfma_f32_16x16x32_bf16 v[102:105], v[148:151], v[226:229], v[102:105]
	v_mfma_f32_16x16x32_bf16 v[98:101], v[156:159], v[226:229], v[98:101]
	v_mfma_f32_16x16x32_bf16 v[86:89], v[148:151], v[234:237], v[86:89]
	v_mfma_f32_16x16x32_bf16 v[82:85], v[156:159], v[234:237], v[82:85]
	v_mfma_f32_16x16x32_bf16 v[110:113], v[160:163], v[206:209], v[110:113]
	v_mfma_f32_16x16x32_bf16 v[106:109], v[182:185], v[206:209], v[106:109]
	v_mfma_f32_16x16x32_bf16 v[94:97], v[160:163], v[214:217], v[94:97]
	v_mfma_f32_16x16x32_bf16 v[90:93], v[182:185], v[214:217], v[90:93]
	v_mfma_f32_16x16x32_bf16 v[78:81], v[160:163], v[222:225], v[78:81]
	v_mfma_f32_16x16x32_bf16 v[74:77], v[182:185], v[222:225], v[74:77]
	v_mfma_f32_16x16x32_bf16 v[70:73], v[160:163], v[230:233], v[70:73]
	v_mfma_f32_16x16x32_bf16 v[66:69], v[182:185], v[230:233], v[66:69]
	v_mfma_f32_16x16x32_bf16 v[110:113], v[178:181], v[210:213], v[110:113]
	v_mfma_f32_16x16x32_bf16 v[106:109], v[186:189], v[210:213], v[106:109]
	v_mfma_f32_16x16x32_bf16 v[94:97], v[178:181], v[218:221], v[94:97]
	v_mfma_f32_16x16x32_bf16 v[90:93], v[186:189], v[218:221], v[90:93]
	v_mfma_f32_16x16x32_bf16 v[78:81], v[178:181], v[226:229], v[78:81]
	v_mfma_f32_16x16x32_bf16 v[74:77], v[186:189], v[226:229], v[74:77]
	v_mfma_f32_16x16x32_bf16 v[70:73], v[178:181], v[234:237], v[70:73]
	v_mfma_f32_16x16x32_bf16 v[66:69], v[186:189], v[234:237], v[66:69]
	s_barrier
	s_setprio 0
	s_add_i32 s46, s62, s71
	v_lshl_add_u64 v[164:165], v[164:165], 0, s[42:43]
	s_mov_b32 m0, s46
	ds_read_b128 v[206:209], v142 offset:49152
	ds_read_b128 v[210:213], v142 offset:50176
	ds_read_b128 v[214:217], v142 offset:51200
	ds_read_b128 v[218:221], v142 offset:52224
	ds_read_b128 v[222:225], v142 offset:53248
	ds_read_b128 v[226:229], v142 offset:54272
	ds_read_b128 v[230:233], v142 offset:55296
	ds_read_b128 v[234:237], v142 offset:56320
	global_load_lds_dwordx4 v[164:165], off
	s_add_i32 m0, s46, 0x2000
	s_add_u32 s46, s60, 0x80080
	v_lshl_add_u64 v[164:165], v[242:243], 0, s[42:43]
	s_addc_u32 s47, s61, 0
	s_add_i32 s60, s63, s71
	global_load_lds_dwordx4 v[164:165], off
	v_lshl_add_u64 v[164:165], s[46:47], 0, v[166:167]
	s_mov_b32 m0, s60
	s_nop 0
	global_load_lds_dwordx4 v[164:165], off
	v_lshl_add_u64 v[164:165], s[46:47], 0, v[130:131]
	s_add_i32 m0, s60, 0x2000
	s_nop 0
	global_load_lds_dwordx4 v[164:165], off
	v_lshl_add_u64 v[164:165], v[244:245], 0, s[42:43]
	s_mov_b32 m0, s76
	s_nop 0
	global_load_lds_dwordx4 v[164:165], off
	v_lshl_add_u64 v[164:165], v[246:247], 0, s[42:43]
	s_mov_b32 m0, s77
	s_nop 0
	global_load_lds_dwordx4 v[164:165], off
	s_waitcnt vmcnt(8)
	s_waitcnt lgkmcnt(0)
	s_setprio 1
	s_waitcnt lgkmcnt(0)
	v_mfma_f32_16x16x32_bf16 v[62:65], v[144:147], v[206:209], v[62:65]
	v_mfma_f32_16x16x32_bf16 v[58:61], v[152:155], v[206:209], v[58:61]
	s_barrier
	v_mfma_f32_16x16x32_bf16 v[54:57], v[144:147], v[214:217], v[54:57]
	v_mfma_f32_16x16x32_bf16 v[50:53], v[152:155], v[214:217], v[50:53]
	v_mfma_f32_16x16x32_bf16 v[38:41], v[144:147], v[222:225], v[38:41]
	v_mfma_f32_16x16x32_bf16 v[34:37], v[152:155], v[222:225], v[34:37]
	v_mfma_f32_16x16x32_bf16 v[22:25], v[144:147], v[230:233], v[22:25]
	v_mfma_f32_16x16x32_bf16 v[18:21], v[152:155], v[230:233], v[18:21]
	v_mfma_f32_16x16x32_bf16 v[62:65], v[148:151], v[210:213], v[62:65]
	v_mfma_f32_16x16x32_bf16 v[58:61], v[156:159], v[210:213], v[58:61]
	v_mfma_f32_16x16x32_bf16 v[54:57], v[148:151], v[218:221], v[54:57]
	v_mfma_f32_16x16x32_bf16 v[50:53], v[156:159], v[218:221], v[50:53]
	v_mfma_f32_16x16x32_bf16 v[38:41], v[148:151], v[226:229], v[38:41]
	v_mfma_f32_16x16x32_bf16 v[34:37], v[156:159], v[226:229], v[34:37]
	v_mfma_f32_16x16x32_bf16 v[22:25], v[148:151], v[234:237], v[22:25]
	v_mfma_f32_16x16x32_bf16 v[18:21], v[156:159], v[234:237], v[18:21]
	v_mfma_f32_16x16x32_bf16 v[46:49], v[160:163], v[206:209], v[46:49]
	v_mfma_f32_16x16x32_bf16 v[42:45], v[182:185], v[206:209], v[42:45]
	v_mfma_f32_16x16x32_bf16 v[30:33], v[160:163], v[214:217], v[30:33]
	v_mfma_f32_16x16x32_bf16 v[26:29], v[182:185], v[214:217], v[26:29]
	v_mfma_f32_16x16x32_bf16 v[14:17], v[160:163], v[222:225], v[14:17]
	v_mfma_f32_16x16x32_bf16 v[10:13], v[182:185], v[222:225], v[10:13]
	v_mfma_f32_16x16x32_bf16 v[6:9], v[160:163], v[230:233], v[6:9]
	v_mfma_f32_16x16x32_bf16 v[2:5], v[182:185], v[230:233], v[2:5]
	v_mfma_f32_16x16x32_bf16 v[46:49], v[178:181], v[210:213], v[46:49]
	v_mfma_f32_16x16x32_bf16 v[42:45], v[186:189], v[210:213], v[42:45]
	v_mfma_f32_16x16x32_bf16 v[30:33], v[178:181], v[218:221], v[30:33]
	v_mfma_f32_16x16x32_bf16 v[26:29], v[186:189], v[218:221], v[26:29]
	v_mfma_f32_16x16x32_bf16 v[14:17], v[178:181], v[226:229], v[14:17]
	v_mfma_f32_16x16x32_bf16 v[10:13], v[186:189], v[226:229], v[10:13]
	v_mfma_f32_16x16x32_bf16 v[6:9], v[178:181], v[234:237], v[6:9]
	v_mfma_f32_16x16x32_bf16 v[2:5], v[186:189], v[234:237], v[2:5]
	s_barrier
	s_setprio 0
	s_add_i32 s82, s82, 2
	s_add_u32 s66, s66, 0x100
	s_addc_u32 s67, s67, 0
	s_add_u32 s80, s80, 0x100
	s_addc_u32 s81, s81, 0
	s_cmp_gt_u32 s82, 29
	s_cbranch_scc0 .LBB0_168
	s_and_b64 vcc, exec, s[10:11]
	s_cbranch_vccz .LBB0_171
	s_barrier

.LBB0_426:
	s_add_u32 s46, s66, 0xfffe0080
	s_addc_u32 s47, s67, -1
	s_add_i32 s62, 0, 0x10000
	s_cmp_eq_u32 s84, 4
	s_cselect_b32 s69, s19, s47
	s_cselect_b32 s68, s80, s46
	v_add_u32_e32 v143, s62, v140
	s_cselect_b32 s61, s17, s83
	s_cselect_b32 s60, s81, s82
	s_add_i32 s63, 0, 0x14000
	ds_read_b128 v[144:147], v143
	ds_read_b128 v[148:151], v143 offset:1024
	ds_read_b128 v[152:155], v143 offset:2048
	ds_read_b128 v[156:159], v143 offset:3072
	v_add_u32_e32 v143, s63, v140
	ds_read_b128 v[160:163], v143
	ds_read_b128 v[178:181], v143 offset:1024
	ds_read_b128 v[182:185], v143 offset:2048
	ds_read_b128 v[186:189], v143 offset:3072
	v_lshl_add_u64 v[164:165], s[66:67], 0, v[136:137]
	s_add_i32 m0, s11, 0xc000
	ds_read_b128 v[206:209], v142
	ds_read_b128 v[210:213], v142 offset:1024
	ds_read_b128 v[214:217], v142 offset:2048
	ds_read_b128 v[218:221], v142 offset:3072
	ds_read_b128 v[222:225], v142 offset:4096
	ds_read_b128 v[226:229], v142 offset:5120
	ds_read_b128 v[230:233], v142 offset:6144
	ds_read_b128 v[234:237], v142 offset:7168
	global_load_lds_dwordx4 v[164:165], off
	v_lshl_add_u64 v[164:165], s[66:67], 0, v[138:139]
	s_add_i32 m0, s11, 0xe000
	s_nop 0
	global_load_lds_dwordx4 v[164:165], off
	s_waitcnt vmcnt(8)
	s_waitcnt lgkmcnt(0)
	s_setprio 1
	s_waitcnt lgkmcnt(0)
	v_mfma_f32_16x16x32_bf16 v[126:129], v[144:147], v[206:209], v[126:129]
	v_mfma_f32_16x16x32_bf16 v[122:125], v[152:155], v[206:209], v[122:125]
	v_mfma_f32_16x16x32_bf16 v[118:121], v[144:147], v[214:217], v[118:121]
	v_mfma_f32_16x16x32_bf16 v[114:117], v[152:155], v[214:217], v[114:117]
	v_mfma_f32_16x16x32_bf16 v[102:105], v[144:147], v[222:225], v[102:105]
	v_mfma_f32_16x16x32_bf16 v[98:101], v[152:155], v[222:225], v[98:101]
	s_barrier
	v_mfma_f32_16x16x32_bf16 v[86:89], v[144:147], v[230:233], v[86:89]
	v_mfma_f32_16x16x32_bf16 v[82:85], v[152:155], v[230:233], v[82:85]
	v_mfma_f32_16x16x32_bf16 v[126:129], v[148:151], v[210:213], v[126:129]
	v_mfma_f32_16x16x32_bf16 v[122:125], v[156:159], v[210:213], v[122:125]
	v_mfma_f32_16x16x32_bf16 v[118:121], v[148:151], v[218:221], v[118:121]
	v_mfma_f32_16x16x32_bf16 v[114:117], v[156:159], v[218:221], v[114:117]
	v_mfma_f32_16x16x32_bf16 v[102:105], v[148:151], v[226:229], v[102:105]
	v_mfma_f32_16x16x32_bf16 v[98:101], v[156:159], v[226:229], v[98:101]
	v_mfma_f32_16x16x32_bf16 v[86:89], v[148:151], v[234:237], v[86:89]
	v_mfma_f32_16x16x32_bf16 v[82:85], v[156:159], v[234:237], v[82:85]
	v_mfma_f32_16x16x32_bf16 v[110:113], v[160:163], v[206:209], v[110:113]
	v_mfma_f32_16x16x32_bf16 v[106:109], v[182:185], v[206:209], v[106:109]
	v_mfma_f32_16x16x32_bf16 v[94:97], v[160:163], v[214:217], v[94:97]
	v_mfma_f32_16x16x32_bf16 v[90:93], v[182:185], v[214:217], v[90:93]
	v_mfma_f32_16x16x32_bf16 v[78:81], v[160:163], v[222:225], v[78:81]
	v_mfma_f32_16x16x32_bf16 v[74:77], v[182:185], v[222:225], v[74:77]
	v_mfma_f32_16x16x32_bf16 v[70:73], v[160:163], v[230:233], v[70:73]
	v_mfma_f32_16x16x32_bf16 v[66:69], v[182:185], v[230:233], v[66:69]
	v_mfma_f32_16x16x32_bf16 v[110:113], v[178:181], v[210:213], v[110:113]
	v_mfma_f32_16x16x32_bf16 v[106:109], v[186:189], v[210:213], v[106:109]
	v_mfma_f32_16x16x32_bf16 v[94:97], v[178:181], v[218:221], v[94:97]
	v_mfma_f32_16x16x32_bf16 v[90:93], v[186:189], v[218:221], v[90:93]
	v_mfma_f32_16x16x32_bf16 v[78:81], v[178:181], v[226:229], v[78:81]
	v_mfma_f32_16x16x32_bf16 v[74:77], v[186:189], v[226:229], v[74:77]
	v_mfma_f32_16x16x32_bf16 v[70:73], v[178:181], v[234:237], v[70:73]
	v_mfma_f32_16x16x32_bf16 v[66:69], v[186:189], v[234:237], v[66:69]
	s_barrier
	s_setprio 0
	s_add_i32 s46, s62, s72
	v_lshl_add_u64 v[164:165], s[60:61], 0, v[166:167]
	s_mov_b32 m0, s46
	ds_read_b128 v[206:209], v142 offset:16384
	ds_read_b128 v[210:213], v142 offset:17408
	ds_read_b128 v[214:217], v142 offset:18432
	ds_read_b128 v[218:221], v142 offset:19456
	ds_read_b128 v[222:225], v142 offset:20480
	ds_read_b128 v[226:229], v142 offset:21504
	ds_read_b128 v[230:233], v142 offset:22528
	ds_read_b128 v[234:237], v142 offset:23552
	global_load_lds_dwordx4 v[164:165], off
	s_add_i32 m0, s46, 0x2000
	s_add_u32 s46, s60, 0x20000
	v_lshl_add_u64 v[242:243], s[60:61], 0, v[130:131]
	s_addc_u32 s47, s61, 0
	s_add_i32 s62, s63, s72
	global_load_lds_dwordx4 v[242:243], off
	v_lshl_add_u64 v[244:245], s[46:47], 0, v[166:167]
	s_mov_b32 m0, s62
	v_lshl_add_u64 v[246:247], s[68:69], 0, v[132:133]
	global_load_lds_dwordx4 v[244:245], off
	v_lshl_add_u64 v[244:245], s[46:47], 0, v[130:131]
	s_add_i32 m0, s62, 0x2000
	s_nop 0
	global_load_lds_dwordx4 v[244:245], off
	v_lshl_add_u64 v[244:245], s[68:69], 0, v[134:135]
	s_mov_b32 m0, s11
	s_nop 0
	global_load_lds_dwordx4 v[244:245], off
	s_mov_b32 m0, s74
	s_nop 0
	global_load_lds_dwordx4 v[246:247], off
	s_waitcnt vmcnt(8)
	s_waitcnt lgkmcnt(0)
	s_setprio 1
	s_waitcnt lgkmcnt(0)
	v_mfma_f32_16x16x32_bf16 v[62:65], v[144:147], v[206:209], v[62:65]
	v_mfma_f32_16x16x32_bf16 v[58:61], v[152:155], v[206:209], v[58:61]
	s_barrier
	v_mfma_f32_16x16x32_bf16 v[54:57], v[144:147], v[214:217], v[54:57]
	v_mfma_f32_16x16x32_bf16 v[50:53], v[152:155], v[214:217], v[50:53]
	v_mfma_f32_16x16x32_bf16 v[38:41], v[144:147], v[222:225], v[38:41]
	v_mfma_f32_16x16x32_bf16 v[34:37], v[152:155], v[222:225], v[34:37]
	v_mfma_f32_16x16x32_bf16 v[22:25], v[144:147], v[230:233], v[22:25]
	v_mfma_f32_16x16x32_bf16 v[18:21], v[152:155], v[230:233], v[18:21]
	v_mfma_f32_16x16x32_bf16 v[62:65], v[148:151], v[210:213], v[62:65]
	v_mfma_f32_16x16x32_bf16 v[58:61], v[156:159], v[210:213], v[58:61]
	v_mfma_f32_16x16x32_bf16 v[54:57], v[148:151], v[218:221], v[54:57]
	v_mfma_f32_16x16x32_bf16 v[50:53], v[156:159], v[218:221], v[50:53]
	v_mfma_f32_16x16x32_bf16 v[38:41], v[148:151], v[226:229], v[38:41]
	v_mfma_f32_16x16x32_bf16 v[34:37], v[156:159], v[226:229], v[34:37]
	v_mfma_f32_16x16x32_bf16 v[22:25], v[148:151], v[234:237], v[22:25]
	v_mfma_f32_16x16x32_bf16 v[18:21], v[156:159], v[234:237], v[18:21]
	v_mfma_f32_16x16x32_bf16 v[46:49], v[160:163], v[206:209], v[46:49]
	v_mfma_f32_16x16x32_bf16 v[42:45], v[182:185], v[206:209], v[42:45]
	v_mfma_f32_16x16x32_bf16 v[30:33], v[160:163], v[214:217], v[30:33]
	v_mfma_f32_16x16x32_bf16 v[26:29], v[182:185], v[214:217], v[26:29]
	v_mfma_f32_16x16x32_bf16 v[14:17], v[160:163], v[222:225], v[14:17]
	v_mfma_f32_16x16x32_bf16 v[10:13], v[182:185], v[222:225], v[10:13]
	v_mfma_f32_16x16x32_bf16 v[6:9], v[160:163], v[230:233], v[6:9]
	v_mfma_f32_16x16x32_bf16 v[2:5], v[182:185], v[230:233], v[2:5]
	v_mfma_f32_16x16x32_bf16 v[46:49], v[178:181], v[210:213], v[46:49]
	v_mfma_f32_16x16x32_bf16 v[42:45], v[186:189], v[210:213], v[42:45]
	v_mfma_f32_16x16x32_bf16 v[30:33], v[178:181], v[218:221], v[30:33]
	v_mfma_f32_16x16x32_bf16 v[26:29], v[186:189], v[218:221], v[26:29]
	v_mfma_f32_16x16x32_bf16 v[14:17], v[178:181], v[226:229], v[14:17]
	v_mfma_f32_16x16x32_bf16 v[10:13], v[186:189], v[226:229], v[10:13]
	v_mfma_f32_16x16x32_bf16 v[6:9], v[178:181], v[234:237], v[6:9]
	v_mfma_f32_16x16x32_bf16 v[2:5], v[186:189], v[234:237], v[2:5]
	s_barrier
	s_setprio 0
	s_add_i32 s62, 0, 0x18000
	v_add_u32_e32 v143, s62, v140
	s_add_i32 s63, 0, 0x1c000
	ds_read_b128 v[144:147], v143
	ds_read_b128 v[148:151], v143 offset:1024
	ds_read_b128 v[152:155], v143 offset:2048
	ds_read_b128 v[156:159], v143 offset:3072
	v_add_u32_e32 v143, s63, v140
	ds_read_b128 v[160:163], v143
	ds_read_b128 v[178:181], v143 offset:1024
	ds_read_b128 v[182:185], v143 offset:2048
	ds_read_b128 v[186:189], v143 offset:3072
	s_add_u32 s46, s68, 0x20000
	s_addc_u32 s47, s69, 0
	s_mov_b32 m0, s75
	v_lshl_add_u64 v[248:249], s[46:47], 0, v[134:135]
	ds_read_b128 v[206:209], v142 offset:32768
	ds_read_b128 v[210:213], v142 offset:33792
	ds_read_b128 v[214:217], v142 offset:34816
	ds_read_b128 v[218:221], v142 offset:35840
	ds_read_b128 v[222:225], v142 offset:36864
	ds_read_b128 v[226:229], v142 offset:37888
	ds_read_b128 v[230:233], v142 offset:38912
	ds_read_b128 v[234:237], v142 offset:39936
	global_load_lds_dwordx4 v[248:249], off
	v_lshl_add_u64 v[248:249], s[46:47], 0, v[132:133]
	s_mov_b32 m0, s76
	s_nop 0
	global_load_lds_dwordx4 v[248:249], off
	s_waitcnt vmcnt(8)
	s_waitcnt lgkmcnt(0)
	s_setprio 1
	s_waitcnt lgkmcnt(0)
	v_mfma_f32_16x16x32_bf16 v[126:129], v[144:147], v[206:209], v[126:129]
	v_mfma_f32_16x16x32_bf16 v[122:125], v[152:155], v[206:209], v[122:125]
	v_mfma_f32_16x16x32_bf16 v[118:121], v[144:147], v[214:217], v[118:121]
	v_mfma_f32_16x16x32_bf16 v[114:117], v[152:155], v[214:217], v[114:117]
	v_mfma_f32_16x16x32_bf16 v[102:105], v[144:147], v[222:225], v[102:105]
	v_mfma_f32_16x16x32_bf16 v[98:101], v[152:155], v[222:225], v[98:101]
	s_barrier
	v_mfma_f32_16x16x32_bf16 v[86:89], v[144:147], v[230:233], v[86:89]
	v_mfma_f32_16x16x32_bf16 v[82:85], v[152:155], v[230:233], v[82:85]
	v_mfma_f32_16x16x32_bf16 v[126:129], v[148:151], v[210:213], v[126:129]
	v_mfma_f32_16x16x32_bf16 v[122:125], v[156:159], v[210:213], v[122:125]
	v_mfma_f32_16x16x32_bf16 v[118:121], v[148:151], v[218:221], v[118:121]
	v_mfma_f32_16x16x32_bf16 v[114:117], v[156:159], v[218:221], v[114:117]
	v_mfma_f32_16x16x32_bf16 v[102:105], v[148:151], v[226:229], v[102:105]
	v_mfma_f32_16x16x32_bf16 v[98:101], v[156:159], v[226:229], v[98:101]
	v_mfma_f32_16x16x32_bf16 v[86:89], v[148:151], v[234:237], v[86:89]
	v_mfma_f32_16x16x32_bf16 v[82:85], v[156:159], v[234:237], v[82:85]
	v_mfma_f32_16x16x32_bf16 v[110:113], v[160:163], v[206:209], v[110:113]
	v_mfma_f32_16x16x32_bf16 v[106:109], v[182:185], v[206:209], v[106:109]
	v_mfma_f32_16x16x32_bf16 v[94:97], v[160:163], v[214:217], v[94:97]
	v_mfma_f32_16x16x32_bf16 v[90:93], v[182:185], v[214:217], v[90:93]
	v_mfma_f32_16x16x32_bf16 v[78:81], v[160:163], v[222:225], v[78:81]
	v_mfma_f32_16x16x32_bf16 v[74:77], v[182:185], v[222:225], v[74:77]
	v_mfma_f32_16x16x32_bf16 v[70:73], v[160:163], v[230:233], v[70:73]
	v_mfma_f32_16x16x32_bf16 v[66:69], v[182:185], v[230:233], v[66:69]
	v_mfma_f32_16x16x32_bf16 v[110:113], v[178:181], v[210:213], v[110:113]
	v_mfma_f32_16x16x32_bf16 v[106:109], v[186:189], v[210:213], v[106:109]
	v_mfma_f32_16x16x32_bf16 v[94:97], v[178:181], v[218:221], v[94:97]
	v_mfma_f32_16x16x32_bf16 v[90:93], v[186:189], v[218:221], v[90:93]
	v_mfma_f32_16x16x32_bf16 v[78:81], v[178:181], v[226:229], v[78:81]
	v_mfma_f32_16x16x32_bf16 v[74:77], v[186:189], v[226:229], v[74:77]
	v_mfma_f32_16x16x32_bf16 v[70:73], v[178:181], v[234:237], v[70:73]
	v_mfma_f32_16x16x32_bf16 v[66:69], v[186:189], v[234:237], v[66:69]
	s_barrier
	s_setprio 0
	s_add_i32 s46, s62, s72
	v_lshl_add_u64 v[164:165], v[164:165], 0, s[42:43]
	s_mov_b32 m0, s46
	ds_read_b128 v[206:209], v142 offset:49152
	ds_read_b128 v[210:213], v142 offset:50176
	ds_read_b128 v[214:217], v142 offset:51200
	ds_read_b128 v[218:221], v142 offset:52224
	ds_read_b128 v[222:225], v142 offset:53248
	ds_read_b128 v[226:229], v142 offset:54272
	ds_read_b128 v[230:233], v142 offset:55296
	ds_read_b128 v[234:237], v142 offset:56320
	global_load_lds_dwordx4 v[164:165], off
	s_add_i32 m0, s46, 0x2000
	s_add_u32 s46, s60, 0x20080
	v_lshl_add_u64 v[164:165], v[242:243], 0, s[42:43]
	s_addc_u32 s47, s61, 0
	s_add_i32 s60, s63, s72
	global_load_lds_dwordx4 v[164:165], off
	v_lshl_add_u64 v[164:165], s[46:47], 0, v[166:167]
	s_mov_b32 m0, s60
	s_nop 0
	global_load_lds_dwordx4 v[164:165], off
	v_lshl_add_u64 v[164:165], s[46:47], 0, v[130:131]
	s_add_i32 m0, s60, 0x2000
	s_nop 0
	global_load_lds_dwordx4 v[164:165], off
	v_lshl_add_u64 v[164:165], v[244:245], 0, s[42:43]
	s_mov_b32 m0, s77
	s_nop 0
	global_load_lds_dwordx4 v[164:165], off
	v_lshl_add_u64 v[164:165], v[246:247], 0, s[42:43]
	s_mov_b32 m0, s78
	s_nop 0
	global_load_lds_dwordx4 v[164:165], off
	s_waitcnt vmcnt(8)
	s_waitcnt lgkmcnt(0)
	s_setprio 1
	s_waitcnt lgkmcnt(0)
	v_mfma_f32_16x16x32_bf16 v[62:65], v[144:147], v[206:209], v[62:65]
	v_mfma_f32_16x16x32_bf16 v[58:61], v[152:155], v[206:209], v[58:61]
	s_barrier
	v_mfma_f32_16x16x32_bf16 v[54:57], v[144:147], v[214:217], v[54:57]
	v_mfma_f32_16x16x32_bf16 v[50:53], v[152:155], v[214:217], v[50:53]
	v_mfma_f32_16x16x32_bf16 v[38:41], v[144:147], v[222:225], v[38:41]
	v_mfma_f32_16x16x32_bf16 v[34:37], v[152:155], v[222:225], v[34:37]
	v_mfma_f32_16x16x32_bf16 v[22:25], v[144:147], v[230:233], v[22:25]
	v_mfma_f32_16x16x32_bf16 v[18:21], v[152:155], v[230:233], v[18:21]
	v_mfma_f32_16x16x32_bf16 v[62:65], v[148:151], v[210:213], v[62:65]
	v_mfma_f32_16x16x32_bf16 v[58:61], v[156:159], v[210:213], v[58:61]
	v_mfma_f32_16x16x32_bf16 v[54:57], v[148:151], v[218:221], v[54:57]
	v_mfma_f32_16x16x32_bf16 v[50:53], v[156:159], v[218:221], v[50:53]
	v_mfma_f32_16x16x32_bf16 v[38:41], v[148:151], v[226:229], v[38:41]
	v_mfma_f32_16x16x32_bf16 v[34:37], v[156:159], v[226:229], v[34:37]
	v_mfma_f32_16x16x32_bf16 v[22:25], v[148:151], v[234:237], v[22:25]
	v_mfma_f32_16x16x32_bf16 v[18:21], v[156:159], v[234:237], v[18:21]
	v_mfma_f32_16x16x32_bf16 v[46:49], v[160:163], v[206:209], v[46:49]
	v_mfma_f32_16x16x32_bf16 v[42:45], v[182:185], v[206:209], v[42:45]
	v_mfma_f32_16x16x32_bf16 v[30:33], v[160:163], v[214:217], v[30:33]
	v_mfma_f32_16x16x32_bf16 v[26:29], v[182:185], v[214:217], v[26:29]
	v_mfma_f32_16x16x32_bf16 v[14:17], v[160:163], v[222:225], v[14:17]
	v_mfma_f32_16x16x32_bf16 v[10:13], v[182:185], v[222:225], v[10:13]
	v_mfma_f32_16x16x32_bf16 v[6:9], v[160:163], v[230:233], v[6:9]
	v_mfma_f32_16x16x32_bf16 v[2:5], v[182:185], v[230:233], v[2:5]
	v_mfma_f32_16x16x32_bf16 v[46:49], v[178:181], v[210:213], v[46:49]
	v_mfma_f32_16x16x32_bf16 v[42:45], v[186:189], v[210:213], v[42:45]
	v_mfma_f32_16x16x32_bf16 v[30:33], v[178:181], v[218:221], v[30:33]
	v_mfma_f32_16x16x32_bf16 v[26:29], v[186:189], v[218:221], v[26:29]
	v_mfma_f32_16x16x32_bf16 v[14:17], v[178:181], v[226:229], v[14:17]
	v_mfma_f32_16x16x32_bf16 v[10:13], v[186:189], v[226:229], v[10:13]
	v_mfma_f32_16x16x32_bf16 v[6:9], v[178:181], v[234:237], v[6:9]
	v_mfma_f32_16x16x32_bf16 v[2:5], v[186:189], v[234:237], v[2:5]
	s_barrier
	s_setprio 0
	s_add_i32 s84, s84, 2
	s_add_u32 s66, s66, 0x100
	s_addc_u32 s67, s67, 0
	s_add_u32 s82, s82, 0x100
	s_addc_u32 s83, s83, 0
	s_cmp_gt_u32 s84, 5
	s_cbranch_scc0 .LBB0_426
	s_and_b64 vcc, exec, s[12:13]
	s_cbranch_vccz .LBB0_429
	s_barrier

.LBB0_442:
	s_add_u32 s62, s18, s72
	s_addc_u32 s63, s19, 0
	s_add_u32 s73, s62, 0x100
	s_addc_u32 s74, s63, 0
	s_and_b64 s[46:47], s[60:61], exec
	s_cselect_b32 s75, s23, s74
	s_cselect_b32 s74, s92, s73
	s_add_u32 s46, s16, s72
	s_addc_u32 s47, s17, 0
	s_add_u32 s72, s46, 0x100
	s_addc_u32 s73, s47, 0
	s_add_i32 s48, 0, 0x10000
	s_and_b64 s[46:47], s[60:61], exec
	s_cselect_b32 s77, s21, s73
	s_cselect_b32 s76, s93, s72
	s_add_i32 s46, 0, 0x14000
	s_add_u32 s80, s62, 0x10080
	s_addc_u32 s81, s63, 0
	s_add_i32 s63, s48, s84
	s_add_i32 m0, s13, 0xc000
	s_add_i32 s49, s13, 0xe000
	s_add_i32 vcc_lo, s63, 0x2000
	v_add_u32_e32 v139, s48, v136
	s_add_u32 s78, s76, 0x10000
	ds_read_b128 v[140:143], v139
	ds_read_b128 v[144:147], v139 offset:1024
	ds_read_b128 v[148:151], v139 offset:2048
	ds_read_b128 v[152:155], v139 offset:3072
	v_add_u32_e32 v139, s46, v136
	s_addc_u32 s79, s77, 0
	s_add_i32 vcc_hi, s46, s84
	ds_read_b128 v[156:159], v139
	ds_read_b128 v[160:163], v139 offset:1024
	ds_read_b128 v[178:181], v139 offset:2048
	ds_read_b128 v[182:185], v139 offset:3072
	s_add_i32 s62, vcc_hi, 0x2000
	s_add_i32 s97, 0, 0x18000
	s_add_i32 s96, 0, 0x1c000
	s_add_u32 s72, s74, 0x10000
	s_addc_u32 s73, s75, 0
	s_add_i32 s95, s97, s84
	s_add_i32 s94, s95, 0x2000
	s_add_u32 s60, s76, 0x10080
	s_addc_u32 s61, s77, 0
	s_add_i32 s47, s96, s84
	s_add_i32 s46, s47, 0x2000
	v_lshl_add_u64 v[164:165], s[80:81], 0, v[134:135]
	ds_read_b128 v[186:189], v138
	ds_read_b128 v[206:209], v138 offset:1024
	ds_read_b128 v[210:213], v138 offset:2048
	ds_read_b128 v[214:217], v138 offset:3072
	ds_read_b128 v[218:221], v138 offset:4096
	ds_read_b128 v[222:225], v138 offset:5120
	ds_read_b128 v[226:229], v138 offset:6144
	ds_read_b128 v[230:233], v138 offset:7168
	global_load_lds_dwordx4 v[164:165], off
	v_lshl_add_u64 v[164:165], s[80:81], 0, v[132:133]
	s_mov_b32 m0, s49
	s_nop 0
	global_load_lds_dwordx4 v[164:165], off
	s_waitcnt vmcnt(8)
	s_waitcnt lgkmcnt(0)
	s_setprio 1
	s_waitcnt lgkmcnt(0)
	v_mfma_f32_16x16x32_bf16 v[126:129], v[140:143], v[186:189], v[126:129]
	v_mfma_f32_16x16x32_bf16 v[122:125], v[148:151], v[186:189], v[122:125]
	v_mfma_f32_16x16x32_bf16 v[118:121], v[140:143], v[210:213], v[118:121]
	v_mfma_f32_16x16x32_bf16 v[114:117], v[148:151], v[210:213], v[114:117]
	v_mfma_f32_16x16x32_bf16 v[102:105], v[140:143], v[218:221], v[102:105]
	v_mfma_f32_16x16x32_bf16 v[98:101], v[148:151], v[218:221], v[98:101]
	s_barrier
	v_mfma_f32_16x16x32_bf16 v[86:89], v[140:143], v[226:229], v[86:89]
	v_mfma_f32_16x16x32_bf16 v[82:85], v[148:151], v[226:229], v[82:85]
	v_mfma_f32_16x16x32_bf16 v[126:129], v[144:147], v[206:209], v[126:129]
	v_mfma_f32_16x16x32_bf16 v[122:125], v[152:155], v[206:209], v[122:125]
	v_mfma_f32_16x16x32_bf16 v[118:121], v[144:147], v[214:217], v[118:121]
	v_mfma_f32_16x16x32_bf16 v[114:117], v[152:155], v[214:217], v[114:117]
	v_mfma_f32_16x16x32_bf16 v[102:105], v[144:147], v[222:225], v[102:105]
	v_mfma_f32_16x16x32_bf16 v[98:101], v[152:155], v[222:225], v[98:101]
	v_mfma_f32_16x16x32_bf16 v[86:89], v[144:147], v[230:233], v[86:89]
	v_mfma_f32_16x16x32_bf16 v[82:85], v[152:155], v[230:233], v[82:85]
	v_mfma_f32_16x16x32_bf16 v[110:113], v[156:159], v[186:189], v[110:113]
	v_mfma_f32_16x16x32_bf16 v[106:109], v[178:181], v[186:189], v[106:109]
	v_mfma_f32_16x16x32_bf16 v[94:97], v[156:159], v[210:213], v[94:97]
	v_mfma_f32_16x16x32_bf16 v[90:93], v[178:181], v[210:213], v[90:93]
	v_mfma_f32_16x16x32_bf16 v[78:81], v[156:159], v[218:221], v[78:81]
	v_mfma_f32_16x16x32_bf16 v[74:77], v[178:181], v[218:221], v[74:77]
	v_mfma_f32_16x16x32_bf16 v[70:73], v[156:159], v[226:229], v[70:73]
	v_mfma_f32_16x16x32_bf16 v[66:69], v[178:181], v[226:229], v[66:69]
	v_mfma_f32_16x16x32_bf16 v[110:113], v[160:163], v[206:209], v[110:113]
	v_mfma_f32_16x16x32_bf16 v[106:109], v[182:185], v[206:209], v[106:109]
	v_mfma_f32_16x16x32_bf16 v[94:97], v[160:163], v[214:217], v[94:97]
	v_mfma_f32_16x16x32_bf16 v[90:93], v[182:185], v[214:217], v[90:93]
	v_mfma_f32_16x16x32_bf16 v[78:81], v[160:163], v[222:225], v[78:81]
	v_mfma_f32_16x16x32_bf16 v[74:77], v[182:185], v[222:225], v[74:77]
	v_mfma_f32_16x16x32_bf16 v[70:73], v[160:163], v[230:233], v[70:73]
	v_mfma_f32_16x16x32_bf16 v[66:69], v[182:185], v[230:233], v[66:69]
	s_barrier
	s_setprio 0
	s_mov_b32 m0, s63
	v_lshl_add_u64 v[164:165], s[76:77], 0, v[166:167]
	ds_read_b128 v[186:189], v138 offset:16384
	ds_read_b128 v[206:209], v138 offset:17408
	ds_read_b128 v[210:213], v138 offset:18432
	ds_read_b128 v[214:217], v138 offset:19456
	ds_read_b128 v[218:221], v138 offset:20480
	ds_read_b128 v[222:225], v138 offset:21504
	ds_read_b128 v[226:229], v138 offset:22528
	ds_read_b128 v[230:233], v138 offset:23552
	global_load_lds_dwordx4 v[164:165], off
	v_lshl_add_u64 v[234:235], s[76:77], 0, v[130:131]
	s_mov_b32 m0, vcc_lo
	v_lshl_add_u64 v[236:237], s[78:79], 0, v[166:167]
	global_load_lds_dwordx4 v[234:235], off
	s_mov_b32 m0, vcc_hi
	v_lshl_add_u64 v[242:243], s[74:75], 0, v[132:133]
	global_load_lds_dwordx4 v[236:237], off
	v_lshl_add_u64 v[236:237], s[78:79], 0, v[130:131]
	s_mov_b32 m0, s62
	s_nop 0
	global_load_lds_dwordx4 v[236:237], off
	v_lshl_add_u64 v[236:237], s[74:75], 0, v[134:135]
	s_mov_b32 m0, s13
	s_nop 0
	global_load_lds_dwordx4 v[236:237], off
	s_mov_b32 m0, s86
	s_nop 0
	global_load_lds_dwordx4 v[242:243], off
	s_waitcnt vmcnt(8)
	s_waitcnt lgkmcnt(0)
	s_setprio 1
	s_waitcnt lgkmcnt(0)
	v_mfma_f32_16x16x32_bf16 v[62:65], v[140:143], v[186:189], v[62:65]
	v_mfma_f32_16x16x32_bf16 v[58:61], v[148:151], v[186:189], v[58:61]
	s_barrier
	v_mfma_f32_16x16x32_bf16 v[54:57], v[140:143], v[210:213], v[54:57]
	v_mfma_f32_16x16x32_bf16 v[50:53], v[148:151], v[210:213], v[50:53]
	v_mfma_f32_16x16x32_bf16 v[38:41], v[140:143], v[218:221], v[38:41]
	v_mfma_f32_16x16x32_bf16 v[34:37], v[148:151], v[218:221], v[34:37]
	v_mfma_f32_16x16x32_bf16 v[22:25], v[140:143], v[226:229], v[22:25]
	v_mfma_f32_16x16x32_bf16 v[18:21], v[148:151], v[226:229], v[18:21]
	v_mfma_f32_16x16x32_bf16 v[62:65], v[144:147], v[206:209], v[62:65]
	v_mfma_f32_16x16x32_bf16 v[58:61], v[152:155], v[206:209], v[58:61]
	v_mfma_f32_16x16x32_bf16 v[54:57], v[144:147], v[214:217], v[54:57]
	v_mfma_f32_16x16x32_bf16 v[50:53], v[152:155], v[214:217], v[50:53]
	v_mfma_f32_16x16x32_bf16 v[38:41], v[144:147], v[222:225], v[38:41]
	v_mfma_f32_16x16x32_bf16 v[34:37], v[152:155], v[222:225], v[34:37]
	v_mfma_f32_16x16x32_bf16 v[22:25], v[144:147], v[230:233], v[22:25]
	v_mfma_f32_16x16x32_bf16 v[18:21], v[152:155], v[230:233], v[18:21]
	v_mfma_f32_16x16x32_bf16 v[46:49], v[156:159], v[186:189], v[46:49]
	v_mfma_f32_16x16x32_bf16 v[42:45], v[178:181], v[186:189], v[42:45]
	v_mfma_f32_16x16x32_bf16 v[30:33], v[156:159], v[210:213], v[30:33]
	v_mfma_f32_16x16x32_bf16 v[26:29], v[178:181], v[210:213], v[26:29]
	v_mfma_f32_16x16x32_bf16 v[14:17], v[156:159], v[218:221], v[14:17]
	v_mfma_f32_16x16x32_bf16 v[10:13], v[178:181], v[218:221], v[10:13]
	v_mfma_f32_16x16x32_bf16 v[6:9], v[156:159], v[226:229], v[6:9]
	v_mfma_f32_16x16x32_bf16 v[2:5], v[178:181], v[226:229], v[2:5]
	v_mfma_f32_16x16x32_bf16 v[46:49], v[160:163], v[206:209], v[46:49]
	v_mfma_f32_16x16x32_bf16 v[42:45], v[182:185], v[206:209], v[42:45]
	v_mfma_f32_16x16x32_bf16 v[30:33], v[160:163], v[214:217], v[30:33]
	v_mfma_f32_16x16x32_bf16 v[26:29], v[182:185], v[214:217], v[26:29]
	v_mfma_f32_16x16x32_bf16 v[14:17], v[160:163], v[222:225], v[14:17]
	v_mfma_f32_16x16x32_bf16 v[10:13], v[182:185], v[222:225], v[10:13]
	v_mfma_f32_16x16x32_bf16 v[6:9], v[160:163], v[230:233], v[6:9]
	v_mfma_f32_16x16x32_bf16 v[2:5], v[182:185], v[230:233], v[2:5]
	s_barrier
	s_setprio 0
	v_add_u32_e32 v139, s97, v136
	ds_read_b128 v[140:143], v139
	ds_read_b128 v[144:147], v139 offset:1024
	ds_read_b128 v[148:151], v139 offset:2048
	ds_read_b128 v[152:155], v139 offset:3072
	v_add_u32_e32 v139, s96, v136
	ds_read_b128 v[156:159], v139
	ds_read_b128 v[160:163], v139 offset:1024
	ds_read_b128 v[178:181], v139 offset:2048
	ds_read_b128 v[182:185], v139 offset:3072
	s_mov_b32 m0, s87
	v_lshl_add_u64 v[244:245], s[72:73], 0, v[134:135]
	ds_read_b128 v[186:189], v138 offset:32768
	ds_read_b128 v[206:209], v138 offset:33792
	ds_read_b128 v[210:213], v138 offset:34816
	ds_read_b128 v[214:217], v138 offset:35840
	ds_read_b128 v[218:221], v138 offset:36864
	ds_read_b128 v[222:225], v138 offset:37888
	ds_read_b128 v[226:229], v138 offset:38912
	ds_read_b128 v[230:233], v138 offset:39936
	global_load_lds_dwordx4 v[244:245], off
	v_lshl_add_u64 v[244:245], s[72:73], 0, v[132:133]
	s_mov_b32 m0, s88
	s_nop 0
	global_load_lds_dwordx4 v[244:245], off
	s_waitcnt vmcnt(8)
	s_waitcnt lgkmcnt(0)
	s_setprio 1
	s_waitcnt lgkmcnt(0)
	v_mfma_f32_16x16x32_bf16 v[126:129], v[140:143], v[186:189], v[126:129]
	v_mfma_f32_16x16x32_bf16 v[122:125], v[148:151], v[186:189], v[122:125]
	v_mfma_f32_16x16x32_bf16 v[118:121], v[140:143], v[210:213], v[118:121]
	v_mfma_f32_16x16x32_bf16 v[114:117], v[148:151], v[210:213], v[114:117]
	v_mfma_f32_16x16x32_bf16 v[102:105], v[140:143], v[218:221], v[102:105]
	v_mfma_f32_16x16x32_bf16 v[98:101], v[148:151], v[218:221], v[98:101]
	s_barrier
	v_mfma_f32_16x16x32_bf16 v[86:89], v[140:143], v[226:229], v[86:89]
	v_mfma_f32_16x16x32_bf16 v[82:85], v[148:151], v[226:229], v[82:85]
	v_mfma_f32_16x16x32_bf16 v[126:129], v[144:147], v[206:209], v[126:129]
	v_mfma_f32_16x16x32_bf16 v[122:125], v[152:155], v[206:209], v[122:125]
	v_mfma_f32_16x16x32_bf16 v[118:121], v[144:147], v[214:217], v[118:121]
	v_mfma_f32_16x16x32_bf16 v[114:117], v[152:155], v[214:217], v[114:117]
	v_mfma_f32_16x16x32_bf16 v[102:105], v[144:147], v[222:225], v[102:105]
	v_mfma_f32_16x16x32_bf16 v[98:101], v[152:155], v[222:225], v[98:101]
	v_mfma_f32_16x16x32_bf16 v[86:89], v[144:147], v[230:233], v[86:89]
	v_mfma_f32_16x16x32_bf16 v[82:85], v[152:155], v[230:233], v[82:85]
	v_mfma_f32_16x16x32_bf16 v[110:113], v[156:159], v[186:189], v[110:113]
	v_mfma_f32_16x16x32_bf16 v[106:109], v[178:181], v[186:189], v[106:109]
	v_mfma_f32_16x16x32_bf16 v[94:97], v[156:159], v[210:213], v[94:97]
	v_mfma_f32_16x16x32_bf16 v[90:93], v[178:181], v[210:213], v[90:93]
	v_mfma_f32_16x16x32_bf16 v[78:81], v[156:159], v[218:221], v[78:81]
	v_mfma_f32_16x16x32_bf16 v[74:77], v[178:181], v[218:221], v[74:77]
	v_mfma_f32_16x16x32_bf16 v[70:73], v[156:159], v[226:229], v[70:73]
	v_mfma_f32_16x16x32_bf16 v[66:69], v[178:181], v[226:229], v[66:69]
	v_mfma_f32_16x16x32_bf16 v[110:113], v[160:163], v[206:209], v[110:113]
	v_mfma_f32_16x16x32_bf16 v[106:109], v[182:185], v[206:209], v[106:109]
	v_mfma_f32_16x16x32_bf16 v[94:97], v[160:163], v[214:217], v[94:97]
	v_mfma_f32_16x16x32_bf16 v[90:93], v[182:185], v[214:217], v[90:93]
	v_mfma_f32_16x16x32_bf16 v[78:81], v[160:163], v[222:225], v[78:81]
	v_mfma_f32_16x16x32_bf16 v[74:77], v[182:185], v[222:225], v[74:77]
	v_mfma_f32_16x16x32_bf16 v[70:73], v[160:163], v[230:233], v[70:73]
	v_mfma_f32_16x16x32_bf16 v[66:69], v[182:185], v[230:233], v[66:69]
	s_barrier
	s_setprio 0
	s_mov_b32 m0, s95
	v_lshl_add_u64 v[164:165], v[164:165], 0, s[42:43]
	ds_read_b128 v[186:189], v138 offset:49152
	ds_read_b128 v[206:209], v138 offset:50176
	ds_read_b128 v[210:213], v138 offset:51200
	ds_read_b128 v[214:217], v138 offset:52224
	ds_read_b128 v[218:221], v138 offset:53248
	ds_read_b128 v[222:225], v138 offset:54272
	ds_read_b128 v[226:229], v138 offset:55296
	ds_read_b128 v[230:233], v138 offset:56320
	global_load_lds_dwordx4 v[164:165], off
	v_lshl_add_u64 v[164:165], v[234:235], 0, s[42:43]
	s_mov_b32 m0, s94
	s_nop 0
	global_load_lds_dwordx4 v[164:165], off
	v_lshl_add_u64 v[164:165], s[60:61], 0, v[166:167]
	s_mov_b32 m0, s47
	s_nop 0
	global_load_lds_dwordx4 v[164:165], off
	v_lshl_add_u64 v[164:165], s[60:61], 0, v[130:131]
	s_mov_b32 m0, s46
	s_nop 0
	global_load_lds_dwordx4 v[164:165], off
	v_lshl_add_u64 v[164:165], v[236:237], 0, s[42:43]
	s_mov_b32 m0, s89
	s_nop 0
	global_load_lds_dwordx4 v[164:165], off
	v_lshl_add_u64 v[164:165], v[242:243], 0, s[42:43]
	s_mov_b32 m0, s90
	s_nop 0
	global_load_lds_dwordx4 v[164:165], off
	s_waitcnt vmcnt(8)
	s_waitcnt lgkmcnt(0)
	s_setprio 1
	s_waitcnt lgkmcnt(0)
	v_mfma_f32_16x16x32_bf16 v[62:65], v[140:143], v[186:189], v[62:65]
	v_mfma_f32_16x16x32_bf16 v[58:61], v[148:151], v[186:189], v[58:61]
	s_barrier
	v_mfma_f32_16x16x32_bf16 v[54:57], v[140:143], v[210:213], v[54:57]
	v_mfma_f32_16x16x32_bf16 v[50:53], v[148:151], v[210:213], v[50:53]
	v_mfma_f32_16x16x32_bf16 v[38:41], v[140:143], v[218:221], v[38:41]
	v_mfma_f32_16x16x32_bf16 v[34:37], v[148:151], v[218:221], v[34:37]
	v_mfma_f32_16x16x32_bf16 v[22:25], v[140:143], v[226:229], v[22:25]
	v_mfma_f32_16x16x32_bf16 v[18:21], v[148:151], v[226:229], v[18:21]
	v_mfma_f32_16x16x32_bf16 v[62:65], v[144:147], v[206:209], v[62:65]
	v_mfma_f32_16x16x32_bf16 v[58:61], v[152:155], v[206:209], v[58:61]
	v_mfma_f32_16x16x32_bf16 v[54:57], v[144:147], v[214:217], v[54:57]
	v_mfma_f32_16x16x32_bf16 v[50:53], v[152:155], v[214:217], v[50:53]
	v_mfma_f32_16x16x32_bf16 v[38:41], v[144:147], v[222:225], v[38:41]
	v_mfma_f32_16x16x32_bf16 v[34:37], v[152:155], v[222:225], v[34:37]
	v_mfma_f32_16x16x32_bf16 v[22:25], v[144:147], v[230:233], v[22:25]
	v_mfma_f32_16x16x32_bf16 v[18:21], v[152:155], v[230:233], v[18:21]
	v_mfma_f32_16x16x32_bf16 v[46:49], v[156:159], v[186:189], v[46:49]
	v_mfma_f32_16x16x32_bf16 v[42:45], v[178:181], v[186:189], v[42:45]
	v_mfma_f32_16x16x32_bf16 v[30:33], v[156:159], v[210:213], v[30:33]
	v_mfma_f32_16x16x32_bf16 v[26:29], v[178:181], v[210:213], v[26:29]
	v_mfma_f32_16x16x32_bf16 v[14:17], v[156:159], v[218:221], v[14:17]
	v_mfma_f32_16x16x32_bf16 v[10:13], v[178:181], v[218:221], v[10:13]
	v_mfma_f32_16x16x32_bf16 v[6:9], v[156:159], v[226:229], v[6:9]
	v_mfma_f32_16x16x32_bf16 v[2:5], v[178:181], v[226:229], v[2:5]
	v_mfma_f32_16x16x32_bf16 v[46:49], v[160:163], v[206:209], v[46:49]
	v_mfma_f32_16x16x32_bf16 v[42:45], v[182:185], v[206:209], v[42:45]
	v_mfma_f32_16x16x32_bf16 v[30:33], v[160:163], v[214:217], v[30:33]
	v_mfma_f32_16x16x32_bf16 v[26:29], v[182:185], v[214:217], v[26:29]
	v_mfma_f32_16x16x32_bf16 v[14:17], v[160:163], v[222:225], v[14:17]
	v_mfma_f32_16x16x32_bf16 v[10:13], v[182:185], v[222:225], v[10:13]
	v_mfma_f32_16x16x32_bf16 v[6:9], v[160:163], v[230:233], v[6:9]
	v_mfma_f32_16x16x32_bf16 v[2:5], v[182:185], v[230:233], v[2:5]
	s_barrier
	s_setprio 0
	s_movk_i32 s72, 0x100
	s_andn2_b64 vcc, exec, s[70:71]
	s_mov_b64 s[60:61], -1
	s_mov_b64 s[70:71], 0
	s_cbranch_vccz .LBB0_442
	s_and_b64 vcc, exec, s[10:11]
	s_cbranch_vccz .LBB0_445
	s_barrier

.LBB0_795:
	s_add_u32 s46, s68, 0xfff80080
	s_addc_u32 s47, s69, -1
	s_add_i32 s48, 0, 0x10000
	s_cmp_eq_u32 s87, 28
	s_cselect_b32 s71, s19, s47
	s_cselect_b32 s70, s83, s46
	s_cselect_b32 s61, s17, s86
	s_cselect_b32 s60, s84, s85
	s_add_i32 s49, 0, 0x14000
	v_add_u32_e32 v156, s48, v1
	v_add_u32_e32 v164, s49, v1
	ds_read_b128 v[130:133], v156
	ds_read_b128 v[134:137], v156 offset:1024
	ds_read_b128 v[150:153], v156 offset:2048
	ds_read_b128 v[156:159], v156 offset:3072
	ds_read_b128 v[160:163], v164
	ds_read_b128 v[178:181], v164 offset:1024
	ds_read_b128 v[182:185], v164 offset:2048
	ds_read_b128 v[186:189], v164 offset:3072
	v_lshl_add_u64 v[164:165], s[68:69], 0, v[146:147]
	s_add_i32 m0, s67, 0xc000
	ds_read_b128 v[206:209], v155
	ds_read_b128 v[210:213], v155 offset:1024
	ds_read_b128 v[214:217], v155 offset:2048
	ds_read_b128 v[218:221], v155 offset:3072
	ds_read_b128 v[222:225], v155 offset:4096
	ds_read_b128 v[226:229], v155 offset:5120
	ds_read_b128 v[230:233], v155 offset:6144
	ds_read_b128 v[234:237], v155 offset:7168
	global_load_lds_dwordx4 v[164:165], off
	v_lshl_add_u64 v[164:165], s[68:69], 0, v[148:149]
	s_add_i32 m0, s67, 0xe000
	s_nop 0
	global_load_lds_dwordx4 v[164:165], off
	s_waitcnt vmcnt(8)
	s_waitcnt lgkmcnt(0)
	s_setprio 1
	s_waitcnt lgkmcnt(0)
	v_mfma_f32_16x16x32_bf16 v[126:129], v[130:133], v[206:209], v[126:129]
	v_mfma_f32_16x16x32_bf16 v[122:125], v[150:153], v[206:209], v[122:125]
	v_mfma_f32_16x16x32_bf16 v[118:121], v[130:133], v[214:217], v[118:121]
	v_mfma_f32_16x16x32_bf16 v[114:117], v[150:153], v[214:217], v[114:117]
	v_mfma_f32_16x16x32_bf16 v[110:113], v[130:133], v[222:225], v[110:113]
	v_mfma_f32_16x16x32_bf16 v[106:109], v[150:153], v[222:225], v[106:109]
	s_barrier
	v_mfma_f32_16x16x32_bf16 v[102:105], v[130:133], v[230:233], v[102:105]
	v_mfma_f32_16x16x32_bf16 v[98:101], v[150:153], v[230:233], v[98:101]
	v_mfma_f32_16x16x32_bf16 v[126:129], v[134:137], v[210:213], v[126:129]
	v_mfma_f32_16x16x32_bf16 v[122:125], v[156:159], v[210:213], v[122:125]
	v_mfma_f32_16x16x32_bf16 v[118:121], v[134:137], v[218:221], v[118:121]
	v_mfma_f32_16x16x32_bf16 v[114:117], v[156:159], v[218:221], v[114:117]
	v_mfma_f32_16x16x32_bf16 v[110:113], v[134:137], v[226:229], v[110:113]
	v_mfma_f32_16x16x32_bf16 v[106:109], v[156:159], v[226:229], v[106:109]
	v_mfma_f32_16x16x32_bf16 v[102:105], v[134:137], v[234:237], v[102:105]
	v_mfma_f32_16x16x32_bf16 v[98:101], v[156:159], v[234:237], v[98:101]
	v_mfma_f32_16x16x32_bf16 v[66:69], v[160:163], v[206:209], v[66:69]
	v_mfma_f32_16x16x32_bf16 v[58:61], v[182:185], v[206:209], v[58:61]
	v_mfma_f32_16x16x32_bf16 v[54:57], v[160:163], v[214:217], v[54:57]
	v_mfma_f32_16x16x32_bf16 v[50:53], v[182:185], v[214:217], v[50:53]
	v_mfma_f32_16x16x32_bf16 v[46:49], v[160:163], v[222:225], v[46:49]
	v_mfma_f32_16x16x32_bf16 v[42:45], v[182:185], v[222:225], v[42:45]
	v_mfma_f32_16x16x32_bf16 v[38:41], v[160:163], v[230:233], v[38:41]
	v_mfma_f32_16x16x32_bf16 v[34:37], v[182:185], v[230:233], v[34:37]
	v_mfma_f32_16x16x32_bf16 v[66:69], v[178:181], v[210:213], v[66:69]
	v_mfma_f32_16x16x32_bf16 v[58:61], v[186:189], v[210:213], v[58:61]
	v_mfma_f32_16x16x32_bf16 v[54:57], v[178:181], v[218:221], v[54:57]
	v_mfma_f32_16x16x32_bf16 v[50:53], v[186:189], v[218:221], v[50:53]
	v_mfma_f32_16x16x32_bf16 v[46:49], v[178:181], v[226:229], v[46:49]
	v_mfma_f32_16x16x32_bf16 v[42:45], v[186:189], v[226:229], v[42:45]
	v_mfma_f32_16x16x32_bf16 v[38:41], v[178:181], v[234:237], v[38:41]
	v_mfma_f32_16x16x32_bf16 v[34:37], v[186:189], v[234:237], v[34:37]
	s_barrier
	s_setprio 0
	s_add_i32 s46, s48, s77
	v_lshl_add_u64 v[164:165], s[60:61], 0, v[166:167]
	s_mov_b32 m0, s46
	ds_read_b128 v[206:209], v155 offset:16384
	ds_read_b128 v[210:213], v155 offset:17408
	ds_read_b128 v[214:217], v155 offset:18432
	ds_read_b128 v[218:221], v155 offset:19456
	ds_read_b128 v[222:225], v155 offset:20480
	ds_read_b128 v[226:229], v155 offset:21504
	ds_read_b128 v[230:233], v155 offset:22528
	ds_read_b128 v[234:237], v155 offset:23552
	global_load_lds_dwordx4 v[164:165], off
	s_add_i32 m0, s46, 0x2000
	s_add_u32 s46, s60, 0x80000
	v_lshl_add_u64 v[242:243], s[60:61], 0, v[142:143]
	s_addc_u32 s47, s61, 0
	s_add_i32 s48, s49, s77
	global_load_lds_dwordx4 v[242:243], off
	v_lshl_add_u64 v[244:245], s[46:47], 0, v[166:167]
	s_mov_b32 m0, s48
	v_lshl_add_u64 v[246:247], s[70:71], 0, v[140:141]
	global_load_lds_dwordx4 v[244:245], off
	v_lshl_add_u64 v[244:245], s[46:47], 0, v[142:143]
	s_add_i32 m0, s48, 0x2000
	s_nop 0
	global_load_lds_dwordx4 v[244:245], off
	v_lshl_add_u64 v[244:245], s[70:71], 0, v[138:139]
	s_mov_b32 m0, s67
	s_nop 0
	global_load_lds_dwordx4 v[244:245], off
	s_mov_b32 m0, s78
	s_nop 0
	global_load_lds_dwordx4 v[246:247], off
	s_waitcnt vmcnt(8)
	s_waitcnt lgkmcnt(0)
	s_setprio 1
	s_waitcnt lgkmcnt(0)
	v_mfma_f32_16x16x32_bf16 v[94:97], v[130:133], v[206:209], v[94:97]
	v_mfma_f32_16x16x32_bf16 v[90:93], v[150:153], v[206:209], v[90:93]
	s_barrier
	v_mfma_f32_16x16x32_bf16 v[86:89], v[130:133], v[214:217], v[86:89]
	v_mfma_f32_16x16x32_bf16 v[82:85], v[150:153], v[214:217], v[82:85]
	v_mfma_f32_16x16x32_bf16 v[78:81], v[130:133], v[222:225], v[78:81]
	v_mfma_f32_16x16x32_bf16 v[74:77], v[150:153], v[222:225], v[74:77]
	v_mfma_f32_16x16x32_bf16 v[70:73], v[130:133], v[230:233], v[70:73]
	v_mfma_f32_16x16x32_bf16 v[62:65], v[150:153], v[230:233], v[62:65]
	v_mfma_f32_16x16x32_bf16 v[94:97], v[134:137], v[210:213], v[94:97]
	v_mfma_f32_16x16x32_bf16 v[90:93], v[156:159], v[210:213], v[90:93]
	v_mfma_f32_16x16x32_bf16 v[86:89], v[134:137], v[218:221], v[86:89]
	v_mfma_f32_16x16x32_bf16 v[82:85], v[156:159], v[218:221], v[82:85]
	v_mfma_f32_16x16x32_bf16 v[78:81], v[134:137], v[226:229], v[78:81]
	v_mfma_f32_16x16x32_bf16 v[74:77], v[156:159], v[226:229], v[74:77]
	v_mfma_f32_16x16x32_bf16 v[70:73], v[134:137], v[234:237], v[70:73]
	v_mfma_f32_16x16x32_bf16 v[62:65], v[156:159], v[234:237], v[62:65]
	v_mfma_f32_16x16x32_bf16 v[30:33], v[160:163], v[206:209], v[30:33]
	v_mfma_f32_16x16x32_bf16 v[26:29], v[182:185], v[206:209], v[26:29]
	v_mfma_f32_16x16x32_bf16 v[22:25], v[160:163], v[214:217], v[22:25]
	v_mfma_f32_16x16x32_bf16 v[18:21], v[182:185], v[214:217], v[18:21]
	v_mfma_f32_16x16x32_bf16 v[14:17], v[160:163], v[222:225], v[14:17]
	v_mfma_f32_16x16x32_bf16 v[10:13], v[182:185], v[222:225], v[10:13]
	v_mfma_f32_16x16x32_bf16 v[6:9], v[160:163], v[230:233], v[6:9]
	v_mfma_f32_16x16x32_bf16 v[2:5], v[182:185], v[230:233], v[2:5]
	v_mfma_f32_16x16x32_bf16 v[30:33], v[178:181], v[210:213], v[30:33]
	v_mfma_f32_16x16x32_bf16 v[26:29], v[186:189], v[210:213], v[26:29]
	v_mfma_f32_16x16x32_bf16 v[22:25], v[178:181], v[218:221], v[22:25]
	v_mfma_f32_16x16x32_bf16 v[18:21], v[186:189], v[218:221], v[18:21]
	v_mfma_f32_16x16x32_bf16 v[14:17], v[178:181], v[226:229], v[14:17]
	v_mfma_f32_16x16x32_bf16 v[10:13], v[186:189], v[226:229], v[10:13]
	v_mfma_f32_16x16x32_bf16 v[6:9], v[178:181], v[234:237], v[6:9]
	v_mfma_f32_16x16x32_bf16 v[2:5], v[186:189], v[234:237], v[2:5]
	s_barrier
	s_setprio 0
	s_add_i32 s48, 0, 0x18000
	s_add_i32 s49, 0, 0x1c000
	v_add_u32_e32 v156, s48, v1
	v_add_u32_e32 v186, s49, v1
	ds_read_b128 v[130:133], v156
	ds_read_b128 v[134:137], v156 offset:1024
	ds_read_b128 v[150:153], v156 offset:2048
	ds_read_b128 v[156:159], v156 offset:3072
	ds_read_b128 v[160:163], v186
	ds_read_b128 v[178:181], v186 offset:1024
	ds_read_b128 v[182:185], v186 offset:2048
	ds_read_b128 v[186:189], v186 offset:3072
	s_add_u32 s46, s70, 0x80000
	s_addc_u32 s47, s71, 0
	s_mov_b32 m0, s79
	v_lshl_add_u64 v[248:249], s[46:47], 0, v[138:139]
	ds_read_b128 v[206:209], v155 offset:32768
	ds_read_b128 v[210:213], v155 offset:33792
	ds_read_b128 v[214:217], v155 offset:34816
	ds_read_b128 v[218:221], v155 offset:35840
	ds_read_b128 v[222:225], v155 offset:36864
	ds_read_b128 v[226:229], v155 offset:37888
	ds_read_b128 v[230:233], v155 offset:38912
	ds_read_b128 v[234:237], v155 offset:39936
	global_load_lds_dwordx4 v[248:249], off
	v_lshl_add_u64 v[248:249], s[46:47], 0, v[140:141]
	s_mov_b32 m0, s80
	s_nop 0
	global_load_lds_dwordx4 v[248:249], off
	s_waitcnt vmcnt(8)
	s_waitcnt lgkmcnt(0)
	s_setprio 1
	s_waitcnt lgkmcnt(0)
	v_mfma_f32_16x16x32_bf16 v[126:129], v[130:133], v[206:209], v[126:129]
	v_mfma_f32_16x16x32_bf16 v[122:125], v[150:153], v[206:209], v[122:125]
	v_mfma_f32_16x16x32_bf16 v[118:121], v[130:133], v[214:217], v[118:121]
	v_mfma_f32_16x16x32_bf16 v[114:117], v[150:153], v[214:217], v[114:117]
	v_mfma_f32_16x16x32_bf16 v[110:113], v[130:133], v[222:225], v[110:113]
	v_mfma_f32_16x16x32_bf16 v[106:109], v[150:153], v[222:225], v[106:109]
	s_barrier
	v_mfma_f32_16x16x32_bf16 v[102:105], v[130:133], v[230:233], v[102:105]
	v_mfma_f32_16x16x32_bf16 v[98:101], v[150:153], v[230:233], v[98:101]
	v_mfma_f32_16x16x32_bf16 v[126:129], v[134:137], v[210:213], v[126:129]
	v_mfma_f32_16x16x32_bf16 v[122:125], v[156:159], v[210:213], v[122:125]
	v_mfma_f32_16x16x32_bf16 v[118:121], v[134:137], v[218:221], v[118:121]
	v_mfma_f32_16x16x32_bf16 v[114:117], v[156:159], v[218:221], v[114:117]
	v_mfma_f32_16x16x32_bf16 v[110:113], v[134:137], v[226:229], v[110:113]
	v_mfma_f32_16x16x32_bf16 v[106:109], v[156:159], v[226:229], v[106:109]
	v_mfma_f32_16x16x32_bf16 v[102:105], v[134:137], v[234:237], v[102:105]
	v_mfma_f32_16x16x32_bf16 v[98:101], v[156:159], v[234:237], v[98:101]
	v_mfma_f32_16x16x32_bf16 v[66:69], v[160:163], v[206:209], v[66:69]
	v_mfma_f32_16x16x32_bf16 v[58:61], v[182:185], v[206:209], v[58:61]
	v_mfma_f32_16x16x32_bf16 v[54:57], v[160:163], v[214:217], v[54:57]
	v_mfma_f32_16x16x32_bf16 v[50:53], v[182:185], v[214:217], v[50:53]
	v_mfma_f32_16x16x32_bf16 v[46:49], v[160:163], v[222:225], v[46:49]
	v_mfma_f32_16x16x32_bf16 v[42:45], v[182:185], v[222:225], v[42:45]
	v_mfma_f32_16x16x32_bf16 v[38:41], v[160:163], v[230:233], v[38:41]
	v_mfma_f32_16x16x32_bf16 v[34:37], v[182:185], v[230:233], v[34:37]
	v_mfma_f32_16x16x32_bf16 v[66:69], v[178:181], v[210:213], v[66:69]
	v_mfma_f32_16x16x32_bf16 v[58:61], v[186:189], v[210:213], v[58:61]
	v_mfma_f32_16x16x32_bf16 v[54:57], v[178:181], v[218:221], v[54:57]
	v_mfma_f32_16x16x32_bf16 v[50:53], v[186:189], v[218:221], v[50:53]
	v_mfma_f32_16x16x32_bf16 v[46:49], v[178:181], v[226:229], v[46:49]
	v_mfma_f32_16x16x32_bf16 v[42:45], v[186:189], v[226:229], v[42:45]
	v_mfma_f32_16x16x32_bf16 v[38:41], v[178:181], v[234:237], v[38:41]
	v_mfma_f32_16x16x32_bf16 v[34:37], v[186:189], v[234:237], v[34:37]
	s_barrier
	s_setprio 0
	s_add_i32 s46, s48, s77
	v_lshl_add_u64 v[164:165], v[164:165], 0, s[42:43]
	s_mov_b32 m0, s46
	ds_read_b128 v[206:209], v155 offset:49152
	ds_read_b128 v[210:213], v155 offset:50176
	ds_read_b128 v[214:217], v155 offset:51200
	ds_read_b128 v[218:221], v155 offset:52224
	ds_read_b128 v[222:225], v155 offset:53248
	ds_read_b128 v[226:229], v155 offset:54272
	ds_read_b128 v[230:233], v155 offset:55296
	ds_read_b128 v[234:237], v155 offset:56320
	global_load_lds_dwordx4 v[164:165], off
	s_add_i32 m0, s46, 0x2000
	s_add_u32 s46, s60, 0x80080
	v_lshl_add_u64 v[164:165], v[242:243], 0, s[42:43]
	s_addc_u32 s47, s61, 0
	s_add_i32 s48, s49, s77
	global_load_lds_dwordx4 v[164:165], off
	v_lshl_add_u64 v[164:165], s[46:47], 0, v[166:167]
	s_mov_b32 m0, s48
	s_nop 0
	global_load_lds_dwordx4 v[164:165], off
	v_lshl_add_u64 v[164:165], s[46:47], 0, v[142:143]
	s_add_i32 m0, s48, 0x2000
	s_nop 0
	global_load_lds_dwordx4 v[164:165], off
	v_lshl_add_u64 v[164:165], v[244:245], 0, s[42:43]
	s_mov_b32 m0, s26
	s_nop 0
	global_load_lds_dwordx4 v[164:165], off
	v_lshl_add_u64 v[164:165], v[246:247], 0, s[42:43]
	s_mov_b32 m0, s81
	s_nop 0
	global_load_lds_dwordx4 v[164:165], off
	s_waitcnt vmcnt(8)
	s_waitcnt lgkmcnt(0)
	s_setprio 1
	s_waitcnt lgkmcnt(0)
	v_mfma_f32_16x16x32_bf16 v[94:97], v[130:133], v[206:209], v[94:97]
	v_mfma_f32_16x16x32_bf16 v[90:93], v[150:153], v[206:209], v[90:93]
	s_barrier
	v_mfma_f32_16x16x32_bf16 v[86:89], v[130:133], v[214:217], v[86:89]
	v_mfma_f32_16x16x32_bf16 v[82:85], v[150:153], v[214:217], v[82:85]
	v_mfma_f32_16x16x32_bf16 v[78:81], v[130:133], v[222:225], v[78:81]
	v_mfma_f32_16x16x32_bf16 v[74:77], v[150:153], v[222:225], v[74:77]
	v_mfma_f32_16x16x32_bf16 v[70:73], v[130:133], v[230:233], v[70:73]
	v_mfma_f32_16x16x32_bf16 v[62:65], v[150:153], v[230:233], v[62:65]
	v_mfma_f32_16x16x32_bf16 v[94:97], v[134:137], v[210:213], v[94:97]
	v_mfma_f32_16x16x32_bf16 v[90:93], v[156:159], v[210:213], v[90:93]
	v_mfma_f32_16x16x32_bf16 v[86:89], v[134:137], v[218:221], v[86:89]
	v_mfma_f32_16x16x32_bf16 v[82:85], v[156:159], v[218:221], v[82:85]
	v_mfma_f32_16x16x32_bf16 v[78:81], v[134:137], v[226:229], v[78:81]
	v_mfma_f32_16x16x32_bf16 v[74:77], v[156:159], v[226:229], v[74:77]
	v_mfma_f32_16x16x32_bf16 v[70:73], v[134:137], v[234:237], v[70:73]
	v_mfma_f32_16x16x32_bf16 v[62:65], v[156:159], v[234:237], v[62:65]
	v_mfma_f32_16x16x32_bf16 v[30:33], v[160:163], v[206:209], v[30:33]
	v_mfma_f32_16x16x32_bf16 v[26:29], v[182:185], v[206:209], v[26:29]
	v_mfma_f32_16x16x32_bf16 v[22:25], v[160:163], v[214:217], v[22:25]
	v_mfma_f32_16x16x32_bf16 v[18:21], v[182:185], v[214:217], v[18:21]
	v_mfma_f32_16x16x32_bf16 v[14:17], v[160:163], v[222:225], v[14:17]
	v_mfma_f32_16x16x32_bf16 v[10:13], v[182:185], v[222:225], v[10:13]
	v_mfma_f32_16x16x32_bf16 v[6:9], v[160:163], v[230:233], v[6:9]
	v_mfma_f32_16x16x32_bf16 v[2:5], v[182:185], v[230:233], v[2:5]
	v_mfma_f32_16x16x32_bf16 v[30:33], v[178:181], v[210:213], v[30:33]
	v_mfma_f32_16x16x32_bf16 v[26:29], v[186:189], v[210:213], v[26:29]
	v_mfma_f32_16x16x32_bf16 v[22:25], v[178:181], v[218:221], v[22:25]
	v_mfma_f32_16x16x32_bf16 v[18:21], v[186:189], v[218:221], v[18:21]
	v_mfma_f32_16x16x32_bf16 v[14:17], v[178:181], v[226:229], v[14:17]
	v_mfma_f32_16x16x32_bf16 v[10:13], v[186:189], v[226:229], v[10:13]
	v_mfma_f32_16x16x32_bf16 v[6:9], v[178:181], v[234:237], v[6:9]
	v_mfma_f32_16x16x32_bf16 v[2:5], v[186:189], v[234:237], v[2:5]
	s_barrier
	s_setprio 0
	s_add_i32 s87, s87, 2
	s_add_u32 s68, s68, 0x100
	s_addc_u32 s69, s69, 0
	s_add_u32 s85, s85, 0x100
	s_addc_u32 s86, s86, 0
	s_cmp_gt_u32 s87, 29
	s_cbranch_scc0 .LBB0_795
	s_and_b64 vcc, exec, s[12:13]
	s_cbranch_vccz .LBB0_798
	s_barrier

.LBB0_819:
	s_add_i32 s93, s60, 2
	s_add_u32 s46, s72, 0x80
	s_addc_u32 s47, s73, 0
	s_add_i32 s48, 0, 0x10000
	s_cmp_eq_u32 s87, s60
	s_cselect_b32 s61, s23, s47
	s_cselect_b32 s60, s64, s46
	s_cselect_b32 s47, s21, s92
	s_cselect_b32 s46, s90, s91
	s_add_i32 s49, 0, 0x14000
	v_add_u32_e32 v142, s48, v205
	v_add_u32_e32 v182, s49, v205
	ds_read_b128 v[130:133], v142
	ds_read_b128 v[134:137], v142 offset:1024
	ds_read_b128 v[138:141], v142 offset:2048
	ds_read_b128 v[142:145], v142 offset:3072
	ds_read_b128 v[146:149], v182
	ds_read_b128 v[150:153], v182 offset:1024
	ds_read_b128 v[178:181], v182 offset:2048
	ds_read_b128 v[182:185], v182 offset:3072
	v_lshl_add_u64 v[236:237], s[72:73], 0, v[162:163]
	s_add_i32 m0, s71, 0xc000
	ds_read_b128 v[186:189], v207
	ds_read_b128 v[208:211], v207 offset:1024
	ds_read_b128 v[212:215], v207 offset:2048
	ds_read_b128 v[216:219], v207 offset:3072
	ds_read_b128 v[220:223], v207 offset:4096
	ds_read_b128 v[224:227], v207 offset:5120
	ds_read_b128 v[228:231], v207 offset:6144
	ds_read_b128 v[232:235], v207 offset:7168
	global_load_lds_dwordx4 v[236:237], off
	v_lshl_add_u64 v[236:237], s[72:73], 0, v[164:165]
	s_add_i32 m0, s71, 0xe000
	s_nop 0
	global_load_lds_dwordx4 v[236:237], off
	s_waitcnt vmcnt(8)
	s_waitcnt lgkmcnt(0)
	s_setprio 1
	s_waitcnt lgkmcnt(0)
	v_mfma_f32_16x16x32_bf16 v[126:129], v[130:133], v[186:189], v[126:129]
	v_mfma_f32_16x16x32_bf16 v[122:125], v[138:141], v[186:189], v[122:125]
	v_mfma_f32_16x16x32_bf16 v[118:121], v[130:133], v[212:215], v[118:121]
	v_mfma_f32_16x16x32_bf16 v[114:117], v[138:141], v[212:215], v[114:117]
	v_mfma_f32_16x16x32_bf16 v[110:113], v[130:133], v[220:223], v[110:113]
	v_mfma_f32_16x16x32_bf16 v[106:109], v[138:141], v[220:223], v[106:109]
	s_barrier
	v_mfma_f32_16x16x32_bf16 v[102:105], v[130:133], v[228:231], v[102:105]
	v_mfma_f32_16x16x32_bf16 v[98:101], v[138:141], v[228:231], v[98:101]
	v_mfma_f32_16x16x32_bf16 v[126:129], v[134:137], v[208:211], v[126:129]
	v_mfma_f32_16x16x32_bf16 v[122:125], v[142:145], v[208:211], v[122:125]
	v_mfma_f32_16x16x32_bf16 v[118:121], v[134:137], v[216:219], v[118:121]
	v_mfma_f32_16x16x32_bf16 v[114:117], v[142:145], v[216:219], v[114:117]
	v_mfma_f32_16x16x32_bf16 v[110:113], v[134:137], v[224:227], v[110:113]
	v_mfma_f32_16x16x32_bf16 v[106:109], v[142:145], v[224:227], v[106:109]
	v_mfma_f32_16x16x32_bf16 v[102:105], v[134:137], v[232:235], v[102:105]
	v_mfma_f32_16x16x32_bf16 v[98:101], v[142:145], v[232:235], v[98:101]
	v_mfma_f32_16x16x32_bf16 v[94:97], v[146:149], v[186:189], v[94:97]
	v_mfma_f32_16x16x32_bf16 v[90:93], v[178:181], v[186:189], v[90:93]
	v_mfma_f32_16x16x32_bf16 v[86:89], v[146:149], v[212:215], v[86:89]
	v_mfma_f32_16x16x32_bf16 v[82:85], v[178:181], v[212:215], v[82:85]
	v_mfma_f32_16x16x32_bf16 v[78:81], v[146:149], v[220:223], v[78:81]
	v_mfma_f32_16x16x32_bf16 v[74:77], v[178:181], v[220:223], v[74:77]
	v_mfma_f32_16x16x32_bf16 v[70:73], v[146:149], v[228:231], v[70:73]
	v_mfma_f32_16x16x32_bf16 v[66:69], v[178:181], v[228:231], v[66:69]
	v_mfma_f32_16x16x32_bf16 v[94:97], v[150:153], v[208:211], v[94:97]
	v_mfma_f32_16x16x32_bf16 v[90:93], v[182:185], v[208:211], v[90:93]
	v_mfma_f32_16x16x32_bf16 v[86:89], v[150:153], v[216:219], v[86:89]
	v_mfma_f32_16x16x32_bf16 v[82:85], v[182:185], v[216:219], v[82:85]
	v_mfma_f32_16x16x32_bf16 v[78:81], v[150:153], v[224:227], v[78:81]
	v_mfma_f32_16x16x32_bf16 v[74:77], v[182:185], v[224:227], v[74:77]
	v_mfma_f32_16x16x32_bf16 v[70:73], v[150:153], v[232:235], v[70:73]
	v_mfma_f32_16x16x32_bf16 v[66:69], v[182:185], v[232:235], v[66:69]
	s_barrier
	s_setprio 0
	s_add_i32 s48, s48, s80
	v_lshl_add_u64 v[236:237], s[46:47], 0, v[166:167]
	s_mov_b32 m0, s48
	ds_read_b128 v[186:189], v207 offset:16384
	ds_read_b128 v[208:211], v207 offset:17408
	ds_read_b128 v[212:215], v207 offset:18432
	ds_read_b128 v[216:219], v207 offset:19456
	ds_read_b128 v[220:223], v207 offset:20480
	ds_read_b128 v[224:227], v207 offset:21504
	ds_read_b128 v[228:231], v207 offset:22528
	ds_read_b128 v[232:235], v207 offset:23552
	global_load_lds_dwordx4 v[236:237], off
	s_add_i32 m0, s48, 0x2000
	v_lshl_add_u64 v[242:243], s[46:47], 0, v[158:159]
	s_add_u32 s46, s46, s26
	s_addc_u32 s47, s47, 0
	s_add_i32 s48, s49, s80
	global_load_lds_dwordx4 v[242:243], off
	v_lshl_add_u64 v[244:245], s[46:47], 0, v[166:167]
	s_mov_b32 m0, s48
	v_lshl_add_u64 v[246:247], s[46:47], 0, v[158:159]
	global_load_lds_dwordx4 v[244:245], off
	s_add_i32 m0, s48, 0x2000
	v_lshl_add_u64 v[248:249], s[60:61], 0, v[154:155]
	global_load_lds_dwordx4 v[246:247], off
	s_mov_b32 m0, s71
	v_lshl_add_u64 v[250:251], s[60:61], 0, v[156:157]
	global_load_lds_dwordx4 v[248:249], off
	s_mov_b32 m0, s81
	s_nop 0
	global_load_lds_dwordx4 v[250:251], off
	s_waitcnt vmcnt(8)
	s_waitcnt lgkmcnt(0)
	s_setprio 1
	s_waitcnt lgkmcnt(0)
	v_mfma_f32_16x16x32_bf16 v[62:65], v[130:133], v[186:189], v[62:65]
	v_mfma_f32_16x16x32_bf16 v[58:61], v[138:141], v[186:189], v[58:61]
	s_barrier
	v_mfma_f32_16x16x32_bf16 v[54:57], v[130:133], v[212:215], v[54:57]
	v_mfma_f32_16x16x32_bf16 v[50:53], v[138:141], v[212:215], v[50:53]
	v_mfma_f32_16x16x32_bf16 v[46:49], v[130:133], v[220:223], v[46:49]
	v_mfma_f32_16x16x32_bf16 v[42:45], v[138:141], v[220:223], v[42:45]
	v_mfma_f32_16x16x32_bf16 v[38:41], v[130:133], v[228:231], v[38:41]
	v_mfma_f32_16x16x32_bf16 v[34:37], v[138:141], v[228:231], v[34:37]
	v_mfma_f32_16x16x32_bf16 v[62:65], v[134:137], v[208:211], v[62:65]
	v_mfma_f32_16x16x32_bf16 v[58:61], v[142:145], v[208:211], v[58:61]
	v_mfma_f32_16x16x32_bf16 v[54:57], v[134:137], v[216:219], v[54:57]
	v_mfma_f32_16x16x32_bf16 v[50:53], v[142:145], v[216:219], v[50:53]
	v_mfma_f32_16x16x32_bf16 v[46:49], v[134:137], v[224:227], v[46:49]
	v_mfma_f32_16x16x32_bf16 v[42:45], v[142:145], v[224:227], v[42:45]
	v_mfma_f32_16x16x32_bf16 v[38:41], v[134:137], v[232:235], v[38:41]
	v_mfma_f32_16x16x32_bf16 v[34:37], v[142:145], v[232:235], v[34:37]
	v_mfma_f32_16x16x32_bf16 v[30:33], v[146:149], v[186:189], v[30:33]
	v_mfma_f32_16x16x32_bf16 v[26:29], v[178:181], v[186:189], v[26:29]
	v_mfma_f32_16x16x32_bf16 v[22:25], v[146:149], v[212:215], v[22:25]
	v_mfma_f32_16x16x32_bf16 v[18:21], v[178:181], v[212:215], v[18:21]
	v_mfma_f32_16x16x32_bf16 v[14:17], v[146:149], v[220:223], v[14:17]
	v_mfma_f32_16x16x32_bf16 v[10:13], v[178:181], v[220:223], v[10:13]
	v_mfma_f32_16x16x32_bf16 v[6:9], v[146:149], v[228:231], v[6:9]
	v_mfma_f32_16x16x32_bf16 v[2:5], v[178:181], v[228:231], v[2:5]
	v_mfma_f32_16x16x32_bf16 v[30:33], v[150:153], v[208:211], v[30:33]
	v_mfma_f32_16x16x32_bf16 v[26:29], v[182:185], v[208:211], v[26:29]
	v_mfma_f32_16x16x32_bf16 v[22:25], v[150:153], v[216:219], v[22:25]
	v_mfma_f32_16x16x32_bf16 v[18:21], v[182:185], v[216:219], v[18:21]
	v_mfma_f32_16x16x32_bf16 v[14:17], v[150:153], v[224:227], v[14:17]
	v_mfma_f32_16x16x32_bf16 v[10:13], v[182:185], v[224:227], v[10:13]
	v_mfma_f32_16x16x32_bf16 v[6:9], v[150:153], v[232:235], v[6:9]
	v_mfma_f32_16x16x32_bf16 v[2:5], v[182:185], v[232:235], v[2:5]
	s_barrier
	s_setprio 0
	s_add_i32 s48, 0, 0x18000
	s_add_i32 s49, 0, 0x1c000
	v_add_u32_e32 v142, s48, v205
	v_add_u32_e32 v182, s49, v205
	ds_read_b128 v[130:133], v142
	ds_read_b128 v[134:137], v142 offset:1024
	ds_read_b128 v[138:141], v142 offset:2048
	ds_read_b128 v[142:145], v142 offset:3072
	ds_read_b128 v[146:149], v182
	ds_read_b128 v[150:153], v182 offset:1024
	ds_read_b128 v[178:181], v182 offset:2048
	ds_read_b128 v[182:185], v182 offset:3072
	s_add_u32 s46, s60, s26
	s_addc_u32 s47, s61, 0
	s_mov_b32 m0, s82
	v_lshl_add_u64 v[252:253], s[46:47], 0, v[154:155]
	ds_read_b128 v[186:189], v207 offset:32768
	ds_read_b128 v[208:211], v207 offset:33792
	ds_read_b128 v[212:215], v207 offset:34816
	ds_read_b128 v[216:219], v207 offset:35840
	ds_read_b128 v[220:223], v207 offset:36864
	ds_read_b128 v[224:227], v207 offset:37888
	ds_read_b128 v[228:231], v207 offset:38912
	ds_read_b128 v[232:235], v207 offset:39936
	global_load_lds_dwordx4 v[252:253], off
	v_lshl_add_u64 v[252:253], s[46:47], 0, v[156:157]
	s_mov_b32 m0, s83
	s_nop 0
	global_load_lds_dwordx4 v[252:253], off
	s_waitcnt vmcnt(8)
	s_waitcnt lgkmcnt(0)
	s_setprio 1
	s_waitcnt lgkmcnt(0)
	v_mfma_f32_16x16x32_bf16 v[126:129], v[130:133], v[186:189], v[126:129]
	v_mfma_f32_16x16x32_bf16 v[122:125], v[138:141], v[186:189], v[122:125]
	v_mfma_f32_16x16x32_bf16 v[118:121], v[130:133], v[212:215], v[118:121]
	v_mfma_f32_16x16x32_bf16 v[114:117], v[138:141], v[212:215], v[114:117]
	v_mfma_f32_16x16x32_bf16 v[110:113], v[130:133], v[220:223], v[110:113]
	v_mfma_f32_16x16x32_bf16 v[106:109], v[138:141], v[220:223], v[106:109]
	s_barrier
	v_mfma_f32_16x16x32_bf16 v[102:105], v[130:133], v[228:231], v[102:105]
	v_mfma_f32_16x16x32_bf16 v[98:101], v[138:141], v[228:231], v[98:101]
	v_mfma_f32_16x16x32_bf16 v[126:129], v[134:137], v[208:211], v[126:129]
	v_mfma_f32_16x16x32_bf16 v[122:125], v[142:145], v[208:211], v[122:125]
	v_mfma_f32_16x16x32_bf16 v[118:121], v[134:137], v[216:219], v[118:121]
	v_mfma_f32_16x16x32_bf16 v[114:117], v[142:145], v[216:219], v[114:117]
	v_mfma_f32_16x16x32_bf16 v[110:113], v[134:137], v[224:227], v[110:113]
	v_mfma_f32_16x16x32_bf16 v[106:109], v[142:145], v[224:227], v[106:109]
	v_mfma_f32_16x16x32_bf16 v[102:105], v[134:137], v[232:235], v[102:105]
	v_mfma_f32_16x16x32_bf16 v[98:101], v[142:145], v[232:235], v[98:101]
	v_mfma_f32_16x16x32_bf16 v[94:97], v[146:149], v[186:189], v[94:97]
	v_mfma_f32_16x16x32_bf16 v[90:93], v[178:181], v[186:189], v[90:93]
	v_mfma_f32_16x16x32_bf16 v[86:89], v[146:149], v[212:215], v[86:89]
	v_mfma_f32_16x16x32_bf16 v[82:85], v[178:181], v[212:215], v[82:85]
	v_mfma_f32_16x16x32_bf16 v[78:81], v[146:149], v[220:223], v[78:81]
	v_mfma_f32_16x16x32_bf16 v[74:77], v[178:181], v[220:223], v[74:77]
	v_mfma_f32_16x16x32_bf16 v[70:73], v[146:149], v[228:231], v[70:73]
	v_mfma_f32_16x16x32_bf16 v[66:69], v[178:181], v[228:231], v[66:69]
	v_mfma_f32_16x16x32_bf16 v[94:97], v[150:153], v[208:211], v[94:97]
	v_mfma_f32_16x16x32_bf16 v[90:93], v[182:185], v[208:211], v[90:93]
	v_mfma_f32_16x16x32_bf16 v[86:89], v[150:153], v[216:219], v[86:89]
	v_mfma_f32_16x16x32_bf16 v[82:85], v[182:185], v[216:219], v[82:85]
	v_mfma_f32_16x16x32_bf16 v[78:81], v[150:153], v[224:227], v[78:81]
	v_mfma_f32_16x16x32_bf16 v[74:77], v[182:185], v[224:227], v[74:77]
	v_mfma_f32_16x16x32_bf16 v[70:73], v[150:153], v[232:235], v[70:73]
	v_mfma_f32_16x16x32_bf16 v[66:69], v[182:185], v[232:235], v[66:69]
	s_barrier
	s_setprio 0
	s_add_i32 s46, s48, s80
	v_lshl_add_u64 v[236:237], v[236:237], 0, s[42:43]
	s_mov_b32 m0, s46
	ds_read_b128 v[186:189], v207 offset:49152
	ds_read_b128 v[208:211], v207 offset:50176
	ds_read_b128 v[212:215], v207 offset:51200
	ds_read_b128 v[216:219], v207 offset:52224
	ds_read_b128 v[220:223], v207 offset:53248
	ds_read_b128 v[224:227], v207 offset:54272
	ds_read_b128 v[228:231], v207 offset:55296
	ds_read_b128 v[232:235], v207 offset:56320
	global_load_lds_dwordx4 v[236:237], off
	v_lshl_add_u64 v[236:237], v[242:243], 0, s[42:43]
	s_add_i32 m0, s46, 0x2000
	s_add_i32 s46, s49, s80
	global_load_lds_dwordx4 v[236:237], off
	v_lshl_add_u64 v[236:237], v[244:245], 0, s[42:43]
	s_mov_b32 m0, s46
	s_nop 0
	global_load_lds_dwordx4 v[236:237], off
	v_lshl_add_u64 v[236:237], v[246:247], 0, s[42:43]
	s_add_i32 m0, s46, 0x2000
	s_nop 0
	global_load_lds_dwordx4 v[236:237], off
	v_lshl_add_u64 v[236:237], v[248:249], 0, s[42:43]
	s_mov_b32 m0, s85
	s_nop 0
	global_load_lds_dwordx4 v[236:237], off
	v_lshl_add_u64 v[236:237], v[250:251], 0, s[42:43]
	s_mov_b32 m0, s86
	s_nop 0
	global_load_lds_dwordx4 v[236:237], off
	s_waitcnt vmcnt(8)
	s_waitcnt lgkmcnt(0)
	s_setprio 1
	s_waitcnt lgkmcnt(0)
	v_mfma_f32_16x16x32_bf16 v[62:65], v[130:133], v[186:189], v[62:65]
	v_mfma_f32_16x16x32_bf16 v[58:61], v[138:141], v[186:189], v[58:61]
	s_barrier
	v_mfma_f32_16x16x32_bf16 v[54:57], v[130:133], v[212:215], v[54:57]
	v_mfma_f32_16x16x32_bf16 v[50:53], v[138:141], v[212:215], v[50:53]
	v_mfma_f32_16x16x32_bf16 v[46:49], v[130:133], v[220:223], v[46:49]
	v_mfma_f32_16x16x32_bf16 v[42:45], v[138:141], v[220:223], v[42:45]
	v_mfma_f32_16x16x32_bf16 v[38:41], v[130:133], v[228:231], v[38:41]
	v_mfma_f32_16x16x32_bf16 v[34:37], v[138:141], v[228:231], v[34:37]
	v_mfma_f32_16x16x32_bf16 v[62:65], v[134:137], v[208:211], v[62:65]
	v_mfma_f32_16x16x32_bf16 v[58:61], v[142:145], v[208:211], v[58:61]
	v_mfma_f32_16x16x32_bf16 v[54:57], v[134:137], v[216:219], v[54:57]
	v_mfma_f32_16x16x32_bf16 v[50:53], v[142:145], v[216:219], v[50:53]
	v_mfma_f32_16x16x32_bf16 v[46:49], v[134:137], v[224:227], v[46:49]
	v_mfma_f32_16x16x32_bf16 v[42:45], v[142:145], v[224:227], v[42:45]
	v_mfma_f32_16x16x32_bf16 v[38:41], v[134:137], v[232:235], v[38:41]
	v_mfma_f32_16x16x32_bf16 v[34:37], v[142:145], v[232:235], v[34:37]
	v_mfma_f32_16x16x32_bf16 v[30:33], v[146:149], v[186:189], v[30:33]
	v_mfma_f32_16x16x32_bf16 v[26:29], v[178:181], v[186:189], v[26:29]
	v_mfma_f32_16x16x32_bf16 v[22:25], v[146:149], v[212:215], v[22:25]
	v_mfma_f32_16x16x32_bf16 v[18:21], v[178:181], v[212:215], v[18:21]
	v_mfma_f32_16x16x32_bf16 v[14:17], v[146:149], v[220:223], v[14:17]
	v_mfma_f32_16x16x32_bf16 v[10:13], v[178:181], v[220:223], v[10:13]
	v_mfma_f32_16x16x32_bf16 v[6:9], v[146:149], v[228:231], v[6:9]
	v_mfma_f32_16x16x32_bf16 v[2:5], v[178:181], v[228:231], v[2:5]
	v_mfma_f32_16x16x32_bf16 v[30:33], v[150:153], v[208:211], v[30:33]
	v_mfma_f32_16x16x32_bf16 v[26:29], v[182:185], v[208:211], v[26:29]
	v_mfma_f32_16x16x32_bf16 v[22:25], v[150:153], v[216:219], v[22:25]
	v_mfma_f32_16x16x32_bf16 v[18:21], v[182:185], v[216:219], v[18:21]
	v_mfma_f32_16x16x32_bf16 v[14:17], v[150:153], v[224:227], v[14:17]
	v_mfma_f32_16x16x32_bf16 v[10:13], v[182:185], v[224:227], v[10:13]
	v_mfma_f32_16x16x32_bf16 v[6:9], v[150:153], v[232:235], v[6:9]
	v_mfma_f32_16x16x32_bf16 v[2:5], v[182:185], v[232:235], v[2:5]
	s_barrier
	s_setprio 0
	s_add_u32 s72, s72, 0x100
	s_addc_u32 s73, s73, 0
	s_add_u32 s91, s91, 0x100
	s_addc_u32 s92, s92, 0
	s_cmp_ge_u32 s93, s84
	s_mov_b32 s60, s93
	s_cbranch_scc0 .LBB0_819
	s_and_b64 vcc, exec, s[18:19]
	s_cbranch_vccz .LBB0_822
	s_barrier

.LBB0_903:
	s_add_u32 s46, s66, 0xfff80080
	s_addc_u32 s47, s67, -1
	s_add_i32 s48, 0, 0x10000
	s_cmp_eq_u32 s84, 28
	s_cselect_b32 s69, s17, s47
	s_cselect_b32 s68, s64, s46
	s_cselect_b32 s61, s13, s83
	s_cselect_b32 s60, s81, s82
	s_add_i32 s49, 0, 0x14000
	v_add_u32_e32 v142, s48, v186
	v_add_u32_e32 v164, s49, v186
	ds_read_b128 v[130:133], v142
	ds_read_b128 v[134:137], v142 offset:1024
	ds_read_b128 v[138:141], v142 offset:2048
	ds_read_b128 v[142:145], v142 offset:3072
	ds_read_b128 v[146:149], v164
	ds_read_b128 v[160:163], v164 offset:1024
	ds_read_b128 v[178:181], v164 offset:2048
	ds_read_b128 v[182:185], v164 offset:3072
	v_lshl_add_u64 v[164:165], s[66:67], 0, v[156:157]
	s_add_i32 m0, s74, 0xc000
	ds_read_b128 v[206:209], v188
	ds_read_b128 v[210:213], v188 offset:1024
	ds_read_b128 v[214:217], v188 offset:2048
	ds_read_b128 v[218:221], v188 offset:3072
	ds_read_b128 v[222:225], v188 offset:4096
	ds_read_b128 v[226:229], v188 offset:5120
	ds_read_b128 v[230:233], v188 offset:6144
	ds_read_b128 v[234:237], v188 offset:7168
	global_load_lds_dwordx4 v[164:165], off
	v_lshl_add_u64 v[164:165], s[66:67], 0, v[158:159]
	s_add_i32 m0, s74, 0xe000
	s_nop 0
	global_load_lds_dwordx4 v[164:165], off
	s_waitcnt vmcnt(8)
	s_waitcnt lgkmcnt(0)
	s_setprio 1
	s_waitcnt lgkmcnt(0)
	v_mfma_f32_16x16x32_bf16 v[126:129], v[130:133], v[206:209], v[126:129]
	v_mfma_f32_16x16x32_bf16 v[122:125], v[138:141], v[206:209], v[122:125]
	v_mfma_f32_16x16x32_bf16 v[118:121], v[130:133], v[214:217], v[118:121]
	v_mfma_f32_16x16x32_bf16 v[110:113], v[138:141], v[214:217], v[110:113]
	v_mfma_f32_16x16x32_bf16 v[94:97], v[130:133], v[222:225], v[94:97]
	v_mfma_f32_16x16x32_bf16 v[90:93], v[138:141], v[222:225], v[90:93]
	s_barrier
	v_mfma_f32_16x16x32_bf16 v[82:85], v[130:133], v[230:233], v[82:85]
	v_mfma_f32_16x16x32_bf16 v[74:77], v[138:141], v[230:233], v[74:77]
	v_mfma_f32_16x16x32_bf16 v[126:129], v[134:137], v[210:213], v[126:129]
	v_mfma_f32_16x16x32_bf16 v[122:125], v[142:145], v[210:213], v[122:125]
	v_mfma_f32_16x16x32_bf16 v[118:121], v[134:137], v[218:221], v[118:121]
	v_mfma_f32_16x16x32_bf16 v[110:113], v[142:145], v[218:221], v[110:113]
	v_mfma_f32_16x16x32_bf16 v[94:97], v[134:137], v[226:229], v[94:97]
	v_mfma_f32_16x16x32_bf16 v[90:93], v[142:145], v[226:229], v[90:93]
	v_mfma_f32_16x16x32_bf16 v[82:85], v[134:137], v[234:237], v[82:85]
	v_mfma_f32_16x16x32_bf16 v[74:77], v[142:145], v[234:237], v[74:77]
	v_mfma_f32_16x16x32_bf16 v[114:117], v[146:149], v[206:209], v[114:117]
	v_mfma_f32_16x16x32_bf16 v[106:109], v[178:181], v[206:209], v[106:109]
	v_mfma_f32_16x16x32_bf16 v[102:105], v[146:149], v[214:217], v[102:105]
	v_mfma_f32_16x16x32_bf16 v[98:101], v[178:181], v[214:217], v[98:101]
	v_mfma_f32_16x16x32_bf16 v[86:89], v[146:149], v[222:225], v[86:89]
	v_mfma_f32_16x16x32_bf16 v[78:81], v[178:181], v[222:225], v[78:81]
	v_mfma_f32_16x16x32_bf16 v[70:73], v[146:149], v[230:233], v[70:73]
	v_mfma_f32_16x16x32_bf16 v[66:69], v[178:181], v[230:233], v[66:69]
	v_mfma_f32_16x16x32_bf16 v[114:117], v[160:163], v[210:213], v[114:117]
	v_mfma_f32_16x16x32_bf16 v[106:109], v[182:185], v[210:213], v[106:109]
	v_mfma_f32_16x16x32_bf16 v[102:105], v[160:163], v[218:221], v[102:105]
	v_mfma_f32_16x16x32_bf16 v[98:101], v[182:185], v[218:221], v[98:101]
	v_mfma_f32_16x16x32_bf16 v[86:89], v[160:163], v[226:229], v[86:89]
	v_mfma_f32_16x16x32_bf16 v[78:81], v[182:185], v[226:229], v[78:81]
	v_mfma_f32_16x16x32_bf16 v[70:73], v[160:163], v[234:237], v[70:73]
	v_mfma_f32_16x16x32_bf16 v[66:69], v[182:185], v[234:237], v[66:69]
	s_barrier
	s_setprio 0
	s_add_i32 s46, s48, s73
	v_lshl_add_u64 v[164:165], s[60:61], 0, v[166:167]
	s_mov_b32 m0, s46
	ds_read_b128 v[206:209], v188 offset:16384
	ds_read_b128 v[210:213], v188 offset:17408
	ds_read_b128 v[214:217], v188 offset:18432
	ds_read_b128 v[218:221], v188 offset:19456
	ds_read_b128 v[222:225], v188 offset:20480
	ds_read_b128 v[226:229], v188 offset:21504
	ds_read_b128 v[230:233], v188 offset:22528
	ds_read_b128 v[234:237], v188 offset:23552
	global_load_lds_dwordx4 v[164:165], off
	s_add_i32 m0, s46, 0x2000
	s_add_u32 s46, s60, 0x80000
	v_lshl_add_u64 v[242:243], s[60:61], 0, v[154:155]
	s_addc_u32 s47, s61, 0
	s_add_i32 s48, s49, s73
	global_load_lds_dwordx4 v[242:243], off
	v_lshl_add_u64 v[244:245], s[46:47], 0, v[166:167]
	s_mov_b32 m0, s48
	v_lshl_add_u64 v[246:247], s[68:69], 0, v[152:153]
	global_load_lds_dwordx4 v[244:245], off
	v_lshl_add_u64 v[244:245], s[46:47], 0, v[154:155]
	s_add_i32 m0, s48, 0x2000
	s_nop 0
	global_load_lds_dwordx4 v[244:245], off
	v_lshl_add_u64 v[244:245], s[68:69], 0, v[150:151]
	s_mov_b32 m0, s74
	s_nop 0
	global_load_lds_dwordx4 v[244:245], off
	s_mov_b32 m0, s75
	s_nop 0
	global_load_lds_dwordx4 v[246:247], off
	s_waitcnt vmcnt(8)
	s_waitcnt lgkmcnt(0)
	s_setprio 1
	s_waitcnt lgkmcnt(0)
	v_mfma_f32_16x16x32_bf16 v[62:65], v[130:133], v[206:209], v[62:65]
	v_mfma_f32_16x16x32_bf16 v[58:61], v[138:141], v[206:209], v[58:61]
	s_barrier
	v_mfma_f32_16x16x32_bf16 v[50:53], v[130:133], v[214:217], v[50:53]
	v_mfma_f32_16x16x32_bf16 v[42:45], v[138:141], v[214:217], v[42:45]
	v_mfma_f32_16x16x32_bf16 v[34:37], v[130:133], v[222:225], v[34:37]
	v_mfma_f32_16x16x32_bf16 v[26:29], v[138:141], v[222:225], v[26:29]
	v_mfma_f32_16x16x32_bf16 v[18:21], v[130:133], v[230:233], v[18:21]
	v_mfma_f32_16x16x32_bf16 v[10:13], v[138:141], v[230:233], v[10:13]
	v_mfma_f32_16x16x32_bf16 v[62:65], v[134:137], v[210:213], v[62:65]
	v_mfma_f32_16x16x32_bf16 v[58:61], v[142:145], v[210:213], v[58:61]
	v_mfma_f32_16x16x32_bf16 v[50:53], v[134:137], v[218:221], v[50:53]
	v_mfma_f32_16x16x32_bf16 v[42:45], v[142:145], v[218:221], v[42:45]
	v_mfma_f32_16x16x32_bf16 v[34:37], v[134:137], v[226:229], v[34:37]
	v_mfma_f32_16x16x32_bf16 v[26:29], v[142:145], v[226:229], v[26:29]
	v_mfma_f32_16x16x32_bf16 v[18:21], v[134:137], v[234:237], v[18:21]
	v_mfma_f32_16x16x32_bf16 v[10:13], v[142:145], v[234:237], v[10:13]
	v_mfma_f32_16x16x32_bf16 v[54:57], v[146:149], v[206:209], v[54:57]
	v_mfma_f32_16x16x32_bf16 v[46:49], v[178:181], v[206:209], v[46:49]
	v_mfma_f32_16x16x32_bf16 v[38:41], v[146:149], v[214:217], v[38:41]
	v_mfma_f32_16x16x32_bf16 v[30:33], v[178:181], v[214:217], v[30:33]
	v_mfma_f32_16x16x32_bf16 v[22:25], v[146:149], v[222:225], v[22:25]
	v_mfma_f32_16x16x32_bf16 v[14:17], v[178:181], v[222:225], v[14:17]
	v_mfma_f32_16x16x32_bf16 v[6:9], v[146:149], v[230:233], v[6:9]
	v_mfma_f32_16x16x32_bf16 v[2:5], v[178:181], v[230:233], v[2:5]
	v_mfma_f32_16x16x32_bf16 v[54:57], v[160:163], v[210:213], v[54:57]
	v_mfma_f32_16x16x32_bf16 v[46:49], v[182:185], v[210:213], v[46:49]
	v_mfma_f32_16x16x32_bf16 v[38:41], v[160:163], v[218:221], v[38:41]
	v_mfma_f32_16x16x32_bf16 v[30:33], v[182:185], v[218:221], v[30:33]
	v_mfma_f32_16x16x32_bf16 v[22:25], v[160:163], v[226:229], v[22:25]
	v_mfma_f32_16x16x32_bf16 v[14:17], v[182:185], v[226:229], v[14:17]
	v_mfma_f32_16x16x32_bf16 v[6:9], v[160:163], v[234:237], v[6:9]
	v_mfma_f32_16x16x32_bf16 v[2:5], v[182:185], v[234:237], v[2:5]
	s_barrier
	s_setprio 0
	s_add_i32 s48, 0, 0x18000
	s_add_i32 s49, 0, 0x1c000
	v_add_u32_e32 v142, s48, v186
	v_add_u32_e32 v182, s49, v186
	ds_read_b128 v[130:133], v142
	ds_read_b128 v[134:137], v142 offset:1024
	ds_read_b128 v[138:141], v142 offset:2048
	ds_read_b128 v[142:145], v142 offset:3072
	ds_read_b128 v[146:149], v182
	ds_read_b128 v[160:163], v182 offset:1024
	ds_read_b128 v[178:181], v182 offset:2048
	ds_read_b128 v[182:185], v182 offset:3072
	s_add_u32 s46, s68, 0x80000
	s_addc_u32 s47, s69, 0
	s_mov_b32 m0, s76
	v_lshl_add_u64 v[248:249], s[46:47], 0, v[150:151]
	ds_read_b128 v[206:209], v188 offset:32768
	ds_read_b128 v[210:213], v188 offset:33792
	ds_read_b128 v[214:217], v188 offset:34816
	ds_read_b128 v[218:221], v188 offset:35840
	ds_read_b128 v[222:225], v188 offset:36864
	ds_read_b128 v[226:229], v188 offset:37888
	ds_read_b128 v[230:233], v188 offset:38912
	ds_read_b128 v[234:237], v188 offset:39936
	global_load_lds_dwordx4 v[248:249], off
	v_lshl_add_u64 v[248:249], s[46:47], 0, v[152:153]
	s_mov_b32 m0, s77
	s_nop 0
	global_load_lds_dwordx4 v[248:249], off
	s_waitcnt vmcnt(8)
	s_waitcnt lgkmcnt(0)
	s_setprio 1
	s_waitcnt lgkmcnt(0)
	v_mfma_f32_16x16x32_bf16 v[126:129], v[130:133], v[206:209], v[126:129]
	v_mfma_f32_16x16x32_bf16 v[122:125], v[138:141], v[206:209], v[122:125]
	v_mfma_f32_16x16x32_bf16 v[118:121], v[130:133], v[214:217], v[118:121]
	v_mfma_f32_16x16x32_bf16 v[110:113], v[138:141], v[214:217], v[110:113]
	v_mfma_f32_16x16x32_bf16 v[94:97], v[130:133], v[222:225], v[94:97]
	v_mfma_f32_16x16x32_bf16 v[90:93], v[138:141], v[222:225], v[90:93]
	s_barrier
	v_mfma_f32_16x16x32_bf16 v[82:85], v[130:133], v[230:233], v[82:85]
	v_mfma_f32_16x16x32_bf16 v[74:77], v[138:141], v[230:233], v[74:77]
	v_mfma_f32_16x16x32_bf16 v[126:129], v[134:137], v[210:213], v[126:129]
	v_mfma_f32_16x16x32_bf16 v[122:125], v[142:145], v[210:213], v[122:125]
	v_mfma_f32_16x16x32_bf16 v[118:121], v[134:137], v[218:221], v[118:121]
	v_mfma_f32_16x16x32_bf16 v[110:113], v[142:145], v[218:221], v[110:113]
	v_mfma_f32_16x16x32_bf16 v[94:97], v[134:137], v[226:229], v[94:97]
	v_mfma_f32_16x16x32_bf16 v[90:93], v[142:145], v[226:229], v[90:93]
	v_mfma_f32_16x16x32_bf16 v[82:85], v[134:137], v[234:237], v[82:85]
	v_mfma_f32_16x16x32_bf16 v[74:77], v[142:145], v[234:237], v[74:77]
	v_mfma_f32_16x16x32_bf16 v[114:117], v[146:149], v[206:209], v[114:117]
	v_mfma_f32_16x16x32_bf16 v[106:109], v[178:181], v[206:209], v[106:109]
	v_mfma_f32_16x16x32_bf16 v[102:105], v[146:149], v[214:217], v[102:105]
	v_mfma_f32_16x16x32_bf16 v[98:101], v[178:181], v[214:217], v[98:101]
	v_mfma_f32_16x16x32_bf16 v[86:89], v[146:149], v[222:225], v[86:89]
	v_mfma_f32_16x16x32_bf16 v[78:81], v[178:181], v[222:225], v[78:81]
	v_mfma_f32_16x16x32_bf16 v[70:73], v[146:149], v[230:233], v[70:73]
	v_mfma_f32_16x16x32_bf16 v[66:69], v[178:181], v[230:233], v[66:69]
	v_mfma_f32_16x16x32_bf16 v[114:117], v[160:163], v[210:213], v[114:117]
	v_mfma_f32_16x16x32_bf16 v[106:109], v[182:185], v[210:213], v[106:109]
	v_mfma_f32_16x16x32_bf16 v[102:105], v[160:163], v[218:221], v[102:105]
	v_mfma_f32_16x16x32_bf16 v[98:101], v[182:185], v[218:221], v[98:101]
	v_mfma_f32_16x16x32_bf16 v[86:89], v[160:163], v[226:229], v[86:89]
	v_mfma_f32_16x16x32_bf16 v[78:81], v[182:185], v[226:229], v[78:81]
	v_mfma_f32_16x16x32_bf16 v[70:73], v[160:163], v[234:237], v[70:73]
	v_mfma_f32_16x16x32_bf16 v[66:69], v[182:185], v[234:237], v[66:69]
	s_barrier
	s_setprio 0
	s_add_i32 s46, s48, s73
	v_lshl_add_u64 v[164:165], v[164:165], 0, s[42:43]
	s_mov_b32 m0, s46
	ds_read_b128 v[206:209], v188 offset:49152
	ds_read_b128 v[210:213], v188 offset:50176
	ds_read_b128 v[214:217], v188 offset:51200
	ds_read_b128 v[218:221], v188 offset:52224
	ds_read_b128 v[222:225], v188 offset:53248
	ds_read_b128 v[226:229], v188 offset:54272
	ds_read_b128 v[230:233], v188 offset:55296
	ds_read_b128 v[234:237], v188 offset:56320
	global_load_lds_dwordx4 v[164:165], off
	s_add_i32 m0, s46, 0x2000
	s_add_u32 s46, s60, 0x80080
	v_lshl_add_u64 v[164:165], v[242:243], 0, s[42:43]
	s_addc_u32 s47, s61, 0
	s_add_i32 s48, s49, s73
	global_load_lds_dwordx4 v[164:165], off
	v_lshl_add_u64 v[164:165], s[46:47], 0, v[166:167]
	s_mov_b32 m0, s48
	s_nop 0
	global_load_lds_dwordx4 v[164:165], off
	v_lshl_add_u64 v[164:165], s[46:47], 0, v[154:155]
	s_add_i32 m0, s48, 0x2000
	s_nop 0
	global_load_lds_dwordx4 v[164:165], off
	v_lshl_add_u64 v[164:165], v[244:245], 0, s[42:43]
	s_mov_b32 m0, s78
	s_nop 0
	global_load_lds_dwordx4 v[164:165], off
	v_lshl_add_u64 v[164:165], v[246:247], 0, s[42:43]
	s_mov_b32 m0, s79
	s_nop 0
	global_load_lds_dwordx4 v[164:165], off
	s_waitcnt vmcnt(8)
	s_waitcnt lgkmcnt(0)
	s_setprio 1
	s_waitcnt lgkmcnt(0)
	v_mfma_f32_16x16x32_bf16 v[62:65], v[130:133], v[206:209], v[62:65]
	v_mfma_f32_16x16x32_bf16 v[58:61], v[138:141], v[206:209], v[58:61]
	s_barrier
	v_mfma_f32_16x16x32_bf16 v[50:53], v[130:133], v[214:217], v[50:53]
	v_mfma_f32_16x16x32_bf16 v[42:45], v[138:141], v[214:217], v[42:45]
	v_mfma_f32_16x16x32_bf16 v[34:37], v[130:133], v[222:225], v[34:37]
	v_mfma_f32_16x16x32_bf16 v[26:29], v[138:141], v[222:225], v[26:29]
	v_mfma_f32_16x16x32_bf16 v[18:21], v[130:133], v[230:233], v[18:21]
	v_mfma_f32_16x16x32_bf16 v[10:13], v[138:141], v[230:233], v[10:13]
	v_mfma_f32_16x16x32_bf16 v[62:65], v[134:137], v[210:213], v[62:65]
	v_mfma_f32_16x16x32_bf16 v[58:61], v[142:145], v[210:213], v[58:61]
	v_mfma_f32_16x16x32_bf16 v[50:53], v[134:137], v[218:221], v[50:53]
	v_mfma_f32_16x16x32_bf16 v[42:45], v[142:145], v[218:221], v[42:45]
	v_mfma_f32_16x16x32_bf16 v[34:37], v[134:137], v[226:229], v[34:37]
	v_mfma_f32_16x16x32_bf16 v[26:29], v[142:145], v[226:229], v[26:29]
	v_mfma_f32_16x16x32_bf16 v[18:21], v[134:137], v[234:237], v[18:21]
	v_mfma_f32_16x16x32_bf16 v[10:13], v[142:145], v[234:237], v[10:13]
	v_mfma_f32_16x16x32_bf16 v[54:57], v[146:149], v[206:209], v[54:57]
	v_mfma_f32_16x16x32_bf16 v[46:49], v[178:181], v[206:209], v[46:49]
	v_mfma_f32_16x16x32_bf16 v[38:41], v[146:149], v[214:217], v[38:41]
	v_mfma_f32_16x16x32_bf16 v[30:33], v[178:181], v[214:217], v[30:33]
	v_mfma_f32_16x16x32_bf16 v[22:25], v[146:149], v[222:225], v[22:25]
	v_mfma_f32_16x16x32_bf16 v[14:17], v[178:181], v[222:225], v[14:17]
	v_mfma_f32_16x16x32_bf16 v[6:9], v[146:149], v[230:233], v[6:9]
	v_mfma_f32_16x16x32_bf16 v[2:5], v[178:181], v[230:233], v[2:5]
	v_mfma_f32_16x16x32_bf16 v[54:57], v[160:163], v[210:213], v[54:57]
	v_mfma_f32_16x16x32_bf16 v[46:49], v[182:185], v[210:213], v[46:49]
	v_mfma_f32_16x16x32_bf16 v[38:41], v[160:163], v[218:221], v[38:41]
	v_mfma_f32_16x16x32_bf16 v[30:33], v[182:185], v[218:221], v[30:33]
	v_mfma_f32_16x16x32_bf16 v[22:25], v[160:163], v[226:229], v[22:25]
	v_mfma_f32_16x16x32_bf16 v[14:17], v[182:185], v[226:229], v[14:17]
	v_mfma_f32_16x16x32_bf16 v[6:9], v[160:163], v[234:237], v[6:9]
	v_mfma_f32_16x16x32_bf16 v[2:5], v[182:185], v[234:237], v[2:5]
	s_barrier
	s_setprio 0
	s_add_i32 s84, s84, 2
	s_add_u32 s66, s66, 0x100
	s_addc_u32 s67, s67, 0
	s_add_u32 s82, s82, 0x100
	s_addc_u32 s83, s83, 0
	s_cmp_gt_u32 s84, 29
	s_cbranch_scc0 .LBB0_903
	s_and_b64 vcc, exec, s[10:11]
	s_cbranch_vccz .LBB0_906
	s_barrier

.LBB0_1035:
	s_add_u32 s46, s64, 0xfff80080
	s_addc_u32 s47, s65, -1
	s_add_i32 s48, 0, 0x10000
	s_cmp_eq_u32 s84, 28
	s_cselect_b32 s67, s17, s47
	s_cselect_b32 s66, s80, s46
	v_add_u32_e32 v140, s48, v142
	s_cselect_b32 s61, s13, s83
	s_cselect_b32 s60, s81, s82
	s_add_i32 s49, 0, 0x14000
	ds_read_b128 v[146:149], v140
	ds_read_b128 v[150:153], v140 offset:1024
	ds_read_b128 v[154:157], v140 offset:2048
	ds_read_b128 v[158:161], v140 offset:3072
	v_add_u32_e32 v140, s49, v142
	ds_read_b128 v[162:165], v140
	ds_read_b128 v[178:181], v140 offset:1024
	ds_read_b128 v[182:185], v140 offset:2048
	ds_read_b128 v[186:189], v140 offset:3072
	v_lshl_add_u64 v[140:141], s[64:65], 0, v[136:137]
	s_add_i32 m0, s23, 0xc000
	ds_read_b128 v[206:209], v144
	ds_read_b128 v[210:213], v144 offset:1024
	ds_read_b128 v[214:217], v144 offset:2048
	ds_read_b128 v[218:221], v144 offset:3072
	ds_read_b128 v[222:225], v144 offset:4096
	ds_read_b128 v[226:229], v144 offset:5120
	ds_read_b128 v[230:233], v144 offset:6144
	ds_read_b128 v[234:237], v144 offset:7168
	global_load_lds_dwordx4 v[140:141], off
	v_lshl_add_u64 v[140:141], s[64:65], 0, v[138:139]
	s_add_i32 m0, s23, 0xe000
	s_nop 0
	global_load_lds_dwordx4 v[140:141], off
	s_waitcnt vmcnt(8)
	s_waitcnt lgkmcnt(0)
	s_setprio 1
	s_waitcnt lgkmcnt(0)
	v_mfma_f32_16x16x32_bf16 v[126:129], v[146:149], v[206:209], v[126:129]
	v_mfma_f32_16x16x32_bf16 v[122:125], v[154:157], v[206:209], v[122:125]
	v_mfma_f32_16x16x32_bf16 v[110:113], v[146:149], v[214:217], v[110:113]
	v_mfma_f32_16x16x32_bf16 v[106:109], v[154:157], v[214:217], v[106:109]
	v_mfma_f32_16x16x32_bf16 v[94:97], v[146:149], v[222:225], v[94:97]
	v_mfma_f32_16x16x32_bf16 v[90:93], v[154:157], v[222:225], v[90:93]
	s_barrier
	v_mfma_f32_16x16x32_bf16 v[78:81], v[146:149], v[230:233], v[78:81]
	v_mfma_f32_16x16x32_bf16 v[74:77], v[154:157], v[230:233], v[74:77]
	v_mfma_f32_16x16x32_bf16 v[126:129], v[150:153], v[210:213], v[126:129]
	v_mfma_f32_16x16x32_bf16 v[122:125], v[158:161], v[210:213], v[122:125]
	v_mfma_f32_16x16x32_bf16 v[110:113], v[150:153], v[218:221], v[110:113]
	v_mfma_f32_16x16x32_bf16 v[106:109], v[158:161], v[218:221], v[106:109]
	v_mfma_f32_16x16x32_bf16 v[94:97], v[150:153], v[226:229], v[94:97]
	v_mfma_f32_16x16x32_bf16 v[90:93], v[158:161], v[226:229], v[90:93]
	v_mfma_f32_16x16x32_bf16 v[78:81], v[150:153], v[234:237], v[78:81]
	v_mfma_f32_16x16x32_bf16 v[74:77], v[158:161], v[234:237], v[74:77]
	v_mfma_f32_16x16x32_bf16 v[118:121], v[162:165], v[206:209], v[118:121]
	v_mfma_f32_16x16x32_bf16 v[114:117], v[182:185], v[206:209], v[114:117]
	v_mfma_f32_16x16x32_bf16 v[102:105], v[162:165], v[214:217], v[102:105]
	v_mfma_f32_16x16x32_bf16 v[98:101], v[182:185], v[214:217], v[98:101]
	v_mfma_f32_16x16x32_bf16 v[86:89], v[162:165], v[222:225], v[86:89]
	v_mfma_f32_16x16x32_bf16 v[82:85], v[182:185], v[222:225], v[82:85]
	v_mfma_f32_16x16x32_bf16 v[70:73], v[162:165], v[230:233], v[70:73]
	v_mfma_f32_16x16x32_bf16 v[66:69], v[182:185], v[230:233], v[66:69]
	v_mfma_f32_16x16x32_bf16 v[118:121], v[178:181], v[210:213], v[118:121]
	v_mfma_f32_16x16x32_bf16 v[114:117], v[186:189], v[210:213], v[114:117]
	v_mfma_f32_16x16x32_bf16 v[102:105], v[178:181], v[218:221], v[102:105]
	v_mfma_f32_16x16x32_bf16 v[98:101], v[186:189], v[218:221], v[98:101]
	v_mfma_f32_16x16x32_bf16 v[86:89], v[178:181], v[226:229], v[86:89]
	v_mfma_f32_16x16x32_bf16 v[82:85], v[186:189], v[226:229], v[82:85]
	v_mfma_f32_16x16x32_bf16 v[70:73], v[178:181], v[234:237], v[70:73]
	v_mfma_f32_16x16x32_bf16 v[66:69], v[186:189], v[234:237], v[66:69]
	s_barrier
	s_setprio 0
	s_add_i32 s46, s48, s72
	v_lshl_add_u64 v[140:141], s[60:61], 0, v[166:167]
	s_mov_b32 m0, s46
	ds_read_b128 v[206:209], v144 offset:16384
	ds_read_b128 v[210:213], v144 offset:17408
	ds_read_b128 v[214:217], v144 offset:18432
	ds_read_b128 v[218:221], v144 offset:19456
	ds_read_b128 v[222:225], v144 offset:20480
	ds_read_b128 v[226:229], v144 offset:21504
	ds_read_b128 v[230:233], v144 offset:22528
	ds_read_b128 v[234:237], v144 offset:23552
	global_load_lds_dwordx4 v[140:141], off
	s_add_i32 m0, s46, 0x2000
	s_add_u32 s46, s60, 0x80000
	v_lshl_add_u64 v[242:243], s[60:61], 0, v[134:135]
	s_addc_u32 s47, s61, 0
	s_add_i32 s48, s49, s72
	global_load_lds_dwordx4 v[242:243], off
	v_lshl_add_u64 v[244:245], s[46:47], 0, v[166:167]
	s_mov_b32 m0, s48
	v_lshl_add_u64 v[246:247], s[66:67], 0, v[132:133]
	global_load_lds_dwordx4 v[244:245], off
	v_lshl_add_u64 v[244:245], s[46:47], 0, v[134:135]
	s_add_i32 m0, s48, 0x2000
	s_nop 0
	global_load_lds_dwordx4 v[244:245], off
	v_lshl_add_u64 v[244:245], s[66:67], 0, v[130:131]
	s_mov_b32 m0, s23
	s_nop 0
	global_load_lds_dwordx4 v[244:245], off
	s_mov_b32 m0, s73
	s_nop 0
	global_load_lds_dwordx4 v[246:247], off
	s_waitcnt vmcnt(8)
	s_waitcnt lgkmcnt(0)
	s_setprio 1
	s_waitcnt lgkmcnt(0)
	v_mfma_f32_16x16x32_bf16 v[62:65], v[146:149], v[206:209], v[62:65]
	v_mfma_f32_16x16x32_bf16 v[58:61], v[154:157], v[206:209], v[58:61]
	s_barrier
	v_mfma_f32_16x16x32_bf16 v[46:49], v[146:149], v[214:217], v[46:49]
	v_mfma_f32_16x16x32_bf16 v[42:45], v[154:157], v[214:217], v[42:45]
	v_mfma_f32_16x16x32_bf16 v[30:33], v[146:149], v[222:225], v[30:33]
	v_mfma_f32_16x16x32_bf16 v[26:29], v[154:157], v[222:225], v[26:29]
	v_mfma_f32_16x16x32_bf16 v[14:17], v[146:149], v[230:233], v[14:17]
	v_mfma_f32_16x16x32_bf16 v[10:13], v[154:157], v[230:233], v[10:13]
	v_mfma_f32_16x16x32_bf16 v[62:65], v[150:153], v[210:213], v[62:65]
	v_mfma_f32_16x16x32_bf16 v[58:61], v[158:161], v[210:213], v[58:61]
	v_mfma_f32_16x16x32_bf16 v[46:49], v[150:153], v[218:221], v[46:49]
	v_mfma_f32_16x16x32_bf16 v[42:45], v[158:161], v[218:221], v[42:45]
	v_mfma_f32_16x16x32_bf16 v[30:33], v[150:153], v[226:229], v[30:33]
	v_mfma_f32_16x16x32_bf16 v[26:29], v[158:161], v[226:229], v[26:29]
	v_mfma_f32_16x16x32_bf16 v[14:17], v[150:153], v[234:237], v[14:17]
	v_mfma_f32_16x16x32_bf16 v[10:13], v[158:161], v[234:237], v[10:13]
	v_mfma_f32_16x16x32_bf16 v[54:57], v[162:165], v[206:209], v[54:57]
	v_mfma_f32_16x16x32_bf16 v[50:53], v[182:185], v[206:209], v[50:53]
	v_mfma_f32_16x16x32_bf16 v[38:41], v[162:165], v[214:217], v[38:41]
	v_mfma_f32_16x16x32_bf16 v[34:37], v[182:185], v[214:217], v[34:37]
	v_mfma_f32_16x16x32_bf16 v[22:25], v[162:165], v[222:225], v[22:25]
	v_mfma_f32_16x16x32_bf16 v[18:21], v[182:185], v[222:225], v[18:21]
	v_mfma_f32_16x16x32_bf16 v[6:9], v[162:165], v[230:233], v[6:9]
	v_mfma_f32_16x16x32_bf16 v[2:5], v[182:185], v[230:233], v[2:5]
	v_mfma_f32_16x16x32_bf16 v[54:57], v[178:181], v[210:213], v[54:57]
	v_mfma_f32_16x16x32_bf16 v[50:53], v[186:189], v[210:213], v[50:53]
	v_mfma_f32_16x16x32_bf16 v[38:41], v[178:181], v[218:221], v[38:41]
	v_mfma_f32_16x16x32_bf16 v[34:37], v[186:189], v[218:221], v[34:37]
	v_mfma_f32_16x16x32_bf16 v[22:25], v[178:181], v[226:229], v[22:25]
	v_mfma_f32_16x16x32_bf16 v[18:21], v[186:189], v[226:229], v[18:21]
	v_mfma_f32_16x16x32_bf16 v[6:9], v[178:181], v[234:237], v[6:9]
	v_mfma_f32_16x16x32_bf16 v[2:5], v[186:189], v[234:237], v[2:5]
	s_barrier
	s_setprio 0
	s_add_i32 s48, 0, 0x18000
	v_add_u32_e32 v145, s48, v142
	s_add_i32 s49, 0, 0x1c000
	ds_read_b128 v[146:149], v145
	ds_read_b128 v[150:153], v145 offset:1024
	ds_read_b128 v[154:157], v145 offset:2048
	ds_read_b128 v[158:161], v145 offset:3072
	v_add_u32_e32 v145, s49, v142
	ds_read_b128 v[162:165], v145
	ds_read_b128 v[178:181], v145 offset:1024
	ds_read_b128 v[182:185], v145 offset:2048
	ds_read_b128 v[186:189], v145 offset:3072
	s_add_u32 s46, s66, 0x80000
	s_addc_u32 s47, s67, 0
	s_mov_b32 m0, s74
	v_lshl_add_u64 v[248:249], s[46:47], 0, v[130:131]
	ds_read_b128 v[206:209], v144 offset:32768
	ds_read_b128 v[210:213], v144 offset:33792
	ds_read_b128 v[214:217], v144 offset:34816
	ds_read_b128 v[218:221], v144 offset:35840
	ds_read_b128 v[222:225], v144 offset:36864
	ds_read_b128 v[226:229], v144 offset:37888
	ds_read_b128 v[230:233], v144 offset:38912
	ds_read_b128 v[234:237], v144 offset:39936
	global_load_lds_dwordx4 v[248:249], off
	v_lshl_add_u64 v[248:249], s[46:47], 0, v[132:133]
	s_mov_b32 m0, s75
	s_nop 0
	global_load_lds_dwordx4 v[248:249], off
	s_waitcnt vmcnt(8)
	s_waitcnt lgkmcnt(0)
	s_setprio 1
	s_waitcnt lgkmcnt(0)
	v_mfma_f32_16x16x32_bf16 v[126:129], v[146:149], v[206:209], v[126:129]
	v_mfma_f32_16x16x32_bf16 v[122:125], v[154:157], v[206:209], v[122:125]
	v_mfma_f32_16x16x32_bf16 v[110:113], v[146:149], v[214:217], v[110:113]
	v_mfma_f32_16x16x32_bf16 v[106:109], v[154:157], v[214:217], v[106:109]
	v_mfma_f32_16x16x32_bf16 v[94:97], v[146:149], v[222:225], v[94:97]
	v_mfma_f32_16x16x32_bf16 v[90:93], v[154:157], v[222:225], v[90:93]
	s_barrier
	v_mfma_f32_16x16x32_bf16 v[78:81], v[146:149], v[230:233], v[78:81]
	v_mfma_f32_16x16x32_bf16 v[74:77], v[154:157], v[230:233], v[74:77]
	v_mfma_f32_16x16x32_bf16 v[126:129], v[150:153], v[210:213], v[126:129]
	v_mfma_f32_16x16x32_bf16 v[122:125], v[158:161], v[210:213], v[122:125]
	v_mfma_f32_16x16x32_bf16 v[110:113], v[150:153], v[218:221], v[110:113]
	v_mfma_f32_16x16x32_bf16 v[106:109], v[158:161], v[218:221], v[106:109]
	v_mfma_f32_16x16x32_bf16 v[94:97], v[150:153], v[226:229], v[94:97]
	v_mfma_f32_16x16x32_bf16 v[90:93], v[158:161], v[226:229], v[90:93]
	v_mfma_f32_16x16x32_bf16 v[78:81], v[150:153], v[234:237], v[78:81]
	v_mfma_f32_16x16x32_bf16 v[74:77], v[158:161], v[234:237], v[74:77]
	v_mfma_f32_16x16x32_bf16 v[118:121], v[162:165], v[206:209], v[118:121]
	v_mfma_f32_16x16x32_bf16 v[114:117], v[182:185], v[206:209], v[114:117]
	v_mfma_f32_16x16x32_bf16 v[102:105], v[162:165], v[214:217], v[102:105]
	v_mfma_f32_16x16x32_bf16 v[98:101], v[182:185], v[214:217], v[98:101]
	v_mfma_f32_16x16x32_bf16 v[86:89], v[162:165], v[222:225], v[86:89]
	v_mfma_f32_16x16x32_bf16 v[82:85], v[182:185], v[222:225], v[82:85]
	v_mfma_f32_16x16x32_bf16 v[70:73], v[162:165], v[230:233], v[70:73]
	v_mfma_f32_16x16x32_bf16 v[66:69], v[182:185], v[230:233], v[66:69]
	v_mfma_f32_16x16x32_bf16 v[118:121], v[178:181], v[210:213], v[118:121]
	v_mfma_f32_16x16x32_bf16 v[114:117], v[186:189], v[210:213], v[114:117]
	v_mfma_f32_16x16x32_bf16 v[102:105], v[178:181], v[218:221], v[102:105]
	v_mfma_f32_16x16x32_bf16 v[98:101], v[186:189], v[218:221], v[98:101]
	v_mfma_f32_16x16x32_bf16 v[86:89], v[178:181], v[226:229], v[86:89]
	v_mfma_f32_16x16x32_bf16 v[82:85], v[186:189], v[226:229], v[82:85]
	v_mfma_f32_16x16x32_bf16 v[70:73], v[178:181], v[234:237], v[70:73]
	v_mfma_f32_16x16x32_bf16 v[66:69], v[186:189], v[234:237], v[66:69]
	s_barrier
	s_setprio 0
	s_add_i32 s46, s48, s72
	v_lshl_add_u64 v[140:141], v[140:141], 0, s[42:43]
	s_mov_b32 m0, s46
	ds_read_b128 v[206:209], v144 offset:49152
	ds_read_b128 v[210:213], v144 offset:50176
	ds_read_b128 v[214:217], v144 offset:51200
	ds_read_b128 v[218:221], v144 offset:52224
	ds_read_b128 v[222:225], v144 offset:53248
	ds_read_b128 v[226:229], v144 offset:54272
	ds_read_b128 v[230:233], v144 offset:55296
	ds_read_b128 v[234:237], v144 offset:56320
	global_load_lds_dwordx4 v[140:141], off
	s_add_i32 m0, s46, 0x2000
	s_add_u32 s46, s60, 0x80080
	v_lshl_add_u64 v[140:141], v[242:243], 0, s[42:43]
	s_addc_u32 s47, s61, 0
	s_add_i32 s48, s49, s72
	global_load_lds_dwordx4 v[140:141], off
	v_lshl_add_u64 v[140:141], s[46:47], 0, v[166:167]
	s_mov_b32 m0, s48
	s_nop 0
	global_load_lds_dwordx4 v[140:141], off
	v_lshl_add_u64 v[140:141], s[46:47], 0, v[134:135]
	s_add_i32 m0, s48, 0x2000
	s_nop 0
	global_load_lds_dwordx4 v[140:141], off
	v_lshl_add_u64 v[140:141], v[244:245], 0, s[42:43]
	s_mov_b32 m0, s76
	s_nop 0
	global_load_lds_dwordx4 v[140:141], off
	v_lshl_add_u64 v[140:141], v[246:247], 0, s[42:43]
	s_mov_b32 m0, s77
	s_nop 0
	global_load_lds_dwordx4 v[140:141], off
	s_waitcnt vmcnt(8)
	s_waitcnt lgkmcnt(0)
	s_setprio 1
	s_waitcnt lgkmcnt(0)
	v_mfma_f32_16x16x32_bf16 v[62:65], v[146:149], v[206:209], v[62:65]
	v_mfma_f32_16x16x32_bf16 v[58:61], v[154:157], v[206:209], v[58:61]
	s_barrier
	v_mfma_f32_16x16x32_bf16 v[46:49], v[146:149], v[214:217], v[46:49]
	v_mfma_f32_16x16x32_bf16 v[42:45], v[154:157], v[214:217], v[42:45]
	v_mfma_f32_16x16x32_bf16 v[30:33], v[146:149], v[222:225], v[30:33]
	v_mfma_f32_16x16x32_bf16 v[26:29], v[154:157], v[222:225], v[26:29]
	v_mfma_f32_16x16x32_bf16 v[14:17], v[146:149], v[230:233], v[14:17]
	v_mfma_f32_16x16x32_bf16 v[10:13], v[154:157], v[230:233], v[10:13]
	v_mfma_f32_16x16x32_bf16 v[62:65], v[150:153], v[210:213], v[62:65]
	v_mfma_f32_16x16x32_bf16 v[58:61], v[158:161], v[210:213], v[58:61]
	v_mfma_f32_16x16x32_bf16 v[46:49], v[150:153], v[218:221], v[46:49]
	v_mfma_f32_16x16x32_bf16 v[42:45], v[158:161], v[218:221], v[42:45]
	v_mfma_f32_16x16x32_bf16 v[30:33], v[150:153], v[226:229], v[30:33]
	v_mfma_f32_16x16x32_bf16 v[26:29], v[158:161], v[226:229], v[26:29]
	v_mfma_f32_16x16x32_bf16 v[14:17], v[150:153], v[234:237], v[14:17]
	v_mfma_f32_16x16x32_bf16 v[10:13], v[158:161], v[234:237], v[10:13]
	v_mfma_f32_16x16x32_bf16 v[54:57], v[162:165], v[206:209], v[54:57]
	v_mfma_f32_16x16x32_bf16 v[50:53], v[182:185], v[206:209], v[50:53]
	v_mfma_f32_16x16x32_bf16 v[38:41], v[162:165], v[214:217], v[38:41]
	v_mfma_f32_16x16x32_bf16 v[34:37], v[182:185], v[214:217], v[34:37]
	v_mfma_f32_16x16x32_bf16 v[22:25], v[162:165], v[222:225], v[22:25]
	v_mfma_f32_16x16x32_bf16 v[18:21], v[182:185], v[222:225], v[18:21]
	v_mfma_f32_16x16x32_bf16 v[6:9], v[162:165], v[230:233], v[6:9]
	v_mfma_f32_16x16x32_bf16 v[2:5], v[182:185], v[230:233], v[2:5]
	v_mfma_f32_16x16x32_bf16 v[54:57], v[178:181], v[210:213], v[54:57]
	v_mfma_f32_16x16x32_bf16 v[50:53], v[186:189], v[210:213], v[50:53]
	v_mfma_f32_16x16x32_bf16 v[38:41], v[178:181], v[218:221], v[38:41]
	v_mfma_f32_16x16x32_bf16 v[34:37], v[186:189], v[218:221], v[34:37]
	v_mfma_f32_16x16x32_bf16 v[22:25], v[178:181], v[226:229], v[22:25]
	v_mfma_f32_16x16x32_bf16 v[18:21], v[186:189], v[226:229], v[18:21]
	v_mfma_f32_16x16x32_bf16 v[6:9], v[178:181], v[234:237], v[6:9]
	v_mfma_f32_16x16x32_bf16 v[2:5], v[186:189], v[234:237], v[2:5]
	s_barrier
	s_setprio 0
	s_add_i32 s84, s84, 2
	s_add_u32 s64, s64, 0x100
	s_addc_u32 s65, s65, 0
	s_add_u32 s82, s82, 0x100
	s_addc_u32 s83, s83, 0
	s_cmp_gt_u32 s84, 29
	s_cbranch_scc0 .LBB0_1035
	s_and_b64 vcc, exec, s[10:11]
	s_cbranch_vccz .LBB0_1038
	s_barrier

.LBB0_1112:
	s_add_u32 s46, s64, 0xffe00080
	s_addc_u32 s47, s65, -1
	s_add_i32 s48, 0, 0x10000
	s_cmpk_eq_i32 s84, 0x7c
	s_cselect_b32 s67, s19, s47
	s_cselect_b32 s66, s80, s46
	s_cselect_b32 s61, s17, s83
	s_cselect_b32 s60, s81, s82
	s_add_i32 s49, 0, 0x14000
	v_add_u32_e32 v142, s48, v182
	v_add_u32_e32 v164, s49, v182
	ds_read_b128 v[130:133], v142
	ds_read_b128 v[134:137], v142 offset:1024
	ds_read_b128 v[138:141], v142 offset:2048
	ds_read_b128 v[142:145], v142 offset:3072
	ds_read_b128 v[146:149], v164
	ds_read_b128 v[160:163], v164 offset:1024
	ds_read_b128 v[178:181], v164 offset:2048
	ds_read_b128 v[186:189], v164 offset:3072
	v_lshl_add_u64 v[164:165], s[64:65], 0, v[156:157]
	s_add_i32 m0, s63, 0xc000
	ds_read_b128 v[206:209], v184
	ds_read_b128 v[210:213], v184 offset:1024
	ds_read_b128 v[214:217], v184 offset:2048
	ds_read_b128 v[218:221], v184 offset:3072
	ds_read_b128 v[222:225], v184 offset:4096
	ds_read_b128 v[226:229], v184 offset:5120
	ds_read_b128 v[230:233], v184 offset:6144
	ds_read_b128 v[234:237], v184 offset:7168
	global_load_lds_dwordx4 v[164:165], off
	v_lshl_add_u64 v[164:165], s[64:65], 0, v[158:159]
	s_add_i32 m0, s63, 0xe000
	s_nop 0
	global_load_lds_dwordx4 v[164:165], off
	s_waitcnt vmcnt(8)
	s_waitcnt lgkmcnt(0)
	s_setprio 1
	s_waitcnt lgkmcnt(0)
	v_mfma_f32_16x16x32_bf16 v[126:129], v[130:133], v[206:209], v[126:129]
	v_mfma_f32_16x16x32_bf16 v[122:125], v[138:141], v[206:209], v[122:125]
	v_mfma_f32_16x16x32_bf16 v[118:121], v[130:133], v[214:217], v[118:121]
	v_mfma_f32_16x16x32_bf16 v[114:117], v[138:141], v[214:217], v[114:117]
	v_mfma_f32_16x16x32_bf16 v[94:97], v[130:133], v[222:225], v[94:97]
	v_mfma_f32_16x16x32_bf16 v[90:93], v[138:141], v[222:225], v[90:93]
	s_barrier
	v_mfma_f32_16x16x32_bf16 v[82:85], v[130:133], v[230:233], v[82:85]
	v_mfma_f32_16x16x32_bf16 v[74:77], v[138:141], v[230:233], v[74:77]
	v_mfma_f32_16x16x32_bf16 v[126:129], v[134:137], v[210:213], v[126:129]
	v_mfma_f32_16x16x32_bf16 v[122:125], v[142:145], v[210:213], v[122:125]
	v_mfma_f32_16x16x32_bf16 v[118:121], v[134:137], v[218:221], v[118:121]
	v_mfma_f32_16x16x32_bf16 v[114:117], v[142:145], v[218:221], v[114:117]
	v_mfma_f32_16x16x32_bf16 v[94:97], v[134:137], v[226:229], v[94:97]
	v_mfma_f32_16x16x32_bf16 v[90:93], v[142:145], v[226:229], v[90:93]
	v_mfma_f32_16x16x32_bf16 v[82:85], v[134:137], v[234:237], v[82:85]
	v_mfma_f32_16x16x32_bf16 v[74:77], v[142:145], v[234:237], v[74:77]
	v_mfma_f32_16x16x32_bf16 v[110:113], v[146:149], v[206:209], v[110:113]
	v_mfma_f32_16x16x32_bf16 v[106:109], v[178:181], v[206:209], v[106:109]
	v_mfma_f32_16x16x32_bf16 v[102:105], v[146:149], v[214:217], v[102:105]
	v_mfma_f32_16x16x32_bf16 v[98:101], v[178:181], v[214:217], v[98:101]
	v_mfma_f32_16x16x32_bf16 v[86:89], v[146:149], v[222:225], v[86:89]
	v_mfma_f32_16x16x32_bf16 v[78:81], v[178:181], v[222:225], v[78:81]
	v_mfma_f32_16x16x32_bf16 v[70:73], v[146:149], v[230:233], v[70:73]
	v_mfma_f32_16x16x32_bf16 v[66:69], v[178:181], v[230:233], v[66:69]
	v_mfma_f32_16x16x32_bf16 v[110:113], v[160:163], v[210:213], v[110:113]
	v_mfma_f32_16x16x32_bf16 v[106:109], v[186:189], v[210:213], v[106:109]
	v_mfma_f32_16x16x32_bf16 v[102:105], v[160:163], v[218:221], v[102:105]
	v_mfma_f32_16x16x32_bf16 v[98:101], v[186:189], v[218:221], v[98:101]
	v_mfma_f32_16x16x32_bf16 v[86:89], v[160:163], v[226:229], v[86:89]
	v_mfma_f32_16x16x32_bf16 v[78:81], v[186:189], v[226:229], v[78:81]
	v_mfma_f32_16x16x32_bf16 v[70:73], v[160:163], v[234:237], v[70:73]
	v_mfma_f32_16x16x32_bf16 v[66:69], v[186:189], v[234:237], v[66:69]
	s_barrier
	s_setprio 0
	s_add_i32 s46, s48, s72
	v_lshl_add_u64 v[164:165], s[60:61], 0, v[166:167]
	s_mov_b32 m0, s46
	ds_read_b128 v[206:209], v184 offset:16384
	ds_read_b128 v[210:213], v184 offset:17408
	ds_read_b128 v[214:217], v184 offset:18432
	ds_read_b128 v[218:221], v184 offset:19456
	ds_read_b128 v[222:225], v184 offset:20480
	ds_read_b128 v[226:229], v184 offset:21504
	ds_read_b128 v[230:233], v184 offset:22528
	ds_read_b128 v[234:237], v184 offset:23552
	global_load_lds_dwordx4 v[164:165], off
	s_add_i32 m0, s46, 0x2000
	s_add_u32 s46, s60, 0x200000
	v_lshl_add_u64 v[242:243], s[60:61], 0, v[154:155]
	s_addc_u32 s47, s61, 0
	s_add_i32 s48, s49, s72
	global_load_lds_dwordx4 v[242:243], off
	v_lshl_add_u64 v[244:245], s[46:47], 0, v[166:167]
	s_mov_b32 m0, s48
	v_lshl_add_u64 v[246:247], s[66:67], 0, v[152:153]
	global_load_lds_dwordx4 v[244:245], off
	v_lshl_add_u64 v[244:245], s[46:47], 0, v[154:155]
	s_add_i32 m0, s48, 0x2000
	s_nop 0
	global_load_lds_dwordx4 v[244:245], off
	v_lshl_add_u64 v[244:245], s[66:67], 0, v[150:151]
	s_mov_b32 m0, s63
	s_nop 0
	global_load_lds_dwordx4 v[244:245], off
	s_mov_b32 m0, s73
	s_nop 0
	global_load_lds_dwordx4 v[246:247], off
	s_waitcnt vmcnt(8)
	s_waitcnt lgkmcnt(0)
	s_setprio 1
	s_waitcnt lgkmcnt(0)
	v_mfma_f32_16x16x32_bf16 v[62:65], v[130:133], v[206:209], v[62:65]
	v_mfma_f32_16x16x32_bf16 v[58:61], v[138:141], v[206:209], v[58:61]
	s_barrier
	v_mfma_f32_16x16x32_bf16 v[50:53], v[130:133], v[214:217], v[50:53]
	v_mfma_f32_16x16x32_bf16 v[42:45], v[138:141], v[214:217], v[42:45]
	v_mfma_f32_16x16x32_bf16 v[34:37], v[130:133], v[222:225], v[34:37]
	v_mfma_f32_16x16x32_bf16 v[26:29], v[138:141], v[222:225], v[26:29]
	v_mfma_f32_16x16x32_bf16 v[18:21], v[130:133], v[230:233], v[18:21]
	v_mfma_f32_16x16x32_bf16 v[10:13], v[138:141], v[230:233], v[10:13]
	v_mfma_f32_16x16x32_bf16 v[62:65], v[134:137], v[210:213], v[62:65]
	v_mfma_f32_16x16x32_bf16 v[58:61], v[142:145], v[210:213], v[58:61]
	v_mfma_f32_16x16x32_bf16 v[50:53], v[134:137], v[218:221], v[50:53]
	v_mfma_f32_16x16x32_bf16 v[42:45], v[142:145], v[218:221], v[42:45]
	v_mfma_f32_16x16x32_bf16 v[34:37], v[134:137], v[226:229], v[34:37]
	v_mfma_f32_16x16x32_bf16 v[26:29], v[142:145], v[226:229], v[26:29]
	v_mfma_f32_16x16x32_bf16 v[18:21], v[134:137], v[234:237], v[18:21]
	v_mfma_f32_16x16x32_bf16 v[10:13], v[142:145], v[234:237], v[10:13]
	v_mfma_f32_16x16x32_bf16 v[54:57], v[146:149], v[206:209], v[54:57]
	v_mfma_f32_16x16x32_bf16 v[46:49], v[178:181], v[206:209], v[46:49]
	v_mfma_f32_16x16x32_bf16 v[38:41], v[146:149], v[214:217], v[38:41]
	v_mfma_f32_16x16x32_bf16 v[30:33], v[178:181], v[214:217], v[30:33]
	v_mfma_f32_16x16x32_bf16 v[22:25], v[146:149], v[222:225], v[22:25]
	v_mfma_f32_16x16x32_bf16 v[14:17], v[178:181], v[222:225], v[14:17]
	v_mfma_f32_16x16x32_bf16 v[6:9], v[146:149], v[230:233], v[6:9]
	v_mfma_f32_16x16x32_bf16 v[2:5], v[178:181], v[230:233], v[2:5]
	v_mfma_f32_16x16x32_bf16 v[54:57], v[160:163], v[210:213], v[54:57]
	v_mfma_f32_16x16x32_bf16 v[46:49], v[186:189], v[210:213], v[46:49]
	v_mfma_f32_16x16x32_bf16 v[38:41], v[160:163], v[218:221], v[38:41]
	v_mfma_f32_16x16x32_bf16 v[30:33], v[186:189], v[218:221], v[30:33]
	v_mfma_f32_16x16x32_bf16 v[22:25], v[160:163], v[226:229], v[22:25]
	v_mfma_f32_16x16x32_bf16 v[14:17], v[186:189], v[226:229], v[14:17]
	v_mfma_f32_16x16x32_bf16 v[6:9], v[160:163], v[234:237], v[6:9]
	v_mfma_f32_16x16x32_bf16 v[2:5], v[186:189], v[234:237], v[2:5]
	s_barrier
	s_setprio 0
	s_add_i32 s48, 0, 0x18000
	s_add_i32 s49, 0, 0x1c000
	v_add_u32_e32 v142, s48, v182
	v_add_u32_e32 v185, s49, v182
	ds_read_b128 v[130:133], v142
	ds_read_b128 v[134:137], v142 offset:1024
	ds_read_b128 v[138:141], v142 offset:2048
	ds_read_b128 v[142:145], v142 offset:3072
	ds_read_b128 v[146:149], v185
	ds_read_b128 v[160:163], v185 offset:1024
	ds_read_b128 v[178:181], v185 offset:2048
	ds_read_b128 v[186:189], v185 offset:3072
	s_add_u32 s46, s66, 0x200000
	s_addc_u32 s47, s67, 0
	s_mov_b32 m0, s74
	v_lshl_add_u64 v[248:249], s[46:47], 0, v[150:151]
	ds_read_b128 v[206:209], v184 offset:32768
	ds_read_b128 v[210:213], v184 offset:33792
	ds_read_b128 v[214:217], v184 offset:34816
	ds_read_b128 v[218:221], v184 offset:35840
	ds_read_b128 v[222:225], v184 offset:36864
	ds_read_b128 v[226:229], v184 offset:37888
	ds_read_b128 v[230:233], v184 offset:38912
	ds_read_b128 v[234:237], v184 offset:39936
	global_load_lds_dwordx4 v[248:249], off
	v_lshl_add_u64 v[248:249], s[46:47], 0, v[152:153]
	s_mov_b32 m0, s75
	s_nop 0
	global_load_lds_dwordx4 v[248:249], off
	s_waitcnt vmcnt(8)
	s_waitcnt lgkmcnt(0)
	s_setprio 1
	s_waitcnt lgkmcnt(0)
	v_mfma_f32_16x16x32_bf16 v[126:129], v[130:133], v[206:209], v[126:129]
	v_mfma_f32_16x16x32_bf16 v[122:125], v[138:141], v[206:209], v[122:125]
	v_mfma_f32_16x16x32_bf16 v[118:121], v[130:133], v[214:217], v[118:121]
	v_mfma_f32_16x16x32_bf16 v[114:117], v[138:141], v[214:217], v[114:117]
	v_mfma_f32_16x16x32_bf16 v[94:97], v[130:133], v[222:225], v[94:97]
	v_mfma_f32_16x16x32_bf16 v[90:93], v[138:141], v[222:225], v[90:93]
	s_barrier
	v_mfma_f32_16x16x32_bf16 v[82:85], v[130:133], v[230:233], v[82:85]
	v_mfma_f32_16x16x32_bf16 v[74:77], v[138:141], v[230:233], v[74:77]
	v_mfma_f32_16x16x32_bf16 v[126:129], v[134:137], v[210:213], v[126:129]
	v_mfma_f32_16x16x32_bf16 v[122:125], v[142:145], v[210:213], v[122:125]
	v_mfma_f32_16x16x32_bf16 v[118:121], v[134:137], v[218:221], v[118:121]
	v_mfma_f32_16x16x32_bf16 v[114:117], v[142:145], v[218:221], v[114:117]
	v_mfma_f32_16x16x32_bf16 v[94:97], v[134:137], v[226:229], v[94:97]
	v_mfma_f32_16x16x32_bf16 v[90:93], v[142:145], v[226:229], v[90:93]
	v_mfma_f32_16x16x32_bf16 v[82:85], v[134:137], v[234:237], v[82:85]
	v_mfma_f32_16x16x32_bf16 v[74:77], v[142:145], v[234:237], v[74:77]
	v_mfma_f32_16x16x32_bf16 v[110:113], v[146:149], v[206:209], v[110:113]
	v_mfma_f32_16x16x32_bf16 v[106:109], v[178:181], v[206:209], v[106:109]
	v_mfma_f32_16x16x32_bf16 v[102:105], v[146:149], v[214:217], v[102:105]
	v_mfma_f32_16x16x32_bf16 v[98:101], v[178:181], v[214:217], v[98:101]
	v_mfma_f32_16x16x32_bf16 v[86:89], v[146:149], v[222:225], v[86:89]
	v_mfma_f32_16x16x32_bf16 v[78:81], v[178:181], v[222:225], v[78:81]
	v_mfma_f32_16x16x32_bf16 v[70:73], v[146:149], v[230:233], v[70:73]
	v_mfma_f32_16x16x32_bf16 v[66:69], v[178:181], v[230:233], v[66:69]
	v_mfma_f32_16x16x32_bf16 v[110:113], v[160:163], v[210:213], v[110:113]
	v_mfma_f32_16x16x32_bf16 v[106:109], v[186:189], v[210:213], v[106:109]
	v_mfma_f32_16x16x32_bf16 v[102:105], v[160:163], v[218:221], v[102:105]
	v_mfma_f32_16x16x32_bf16 v[98:101], v[186:189], v[218:221], v[98:101]
	v_mfma_f32_16x16x32_bf16 v[86:89], v[160:163], v[226:229], v[86:89]
	v_mfma_f32_16x16x32_bf16 v[78:81], v[186:189], v[226:229], v[78:81]
	v_mfma_f32_16x16x32_bf16 v[70:73], v[160:163], v[234:237], v[70:73]
	v_mfma_f32_16x16x32_bf16 v[66:69], v[186:189], v[234:237], v[66:69]
	s_barrier
	s_setprio 0
	s_add_i32 s46, s48, s72
	v_lshl_add_u64 v[164:165], v[164:165], 0, s[42:43]
	s_mov_b32 m0, s46
	ds_read_b128 v[206:209], v184 offset:49152
	ds_read_b128 v[210:213], v184 offset:50176
	ds_read_b128 v[214:217], v184 offset:51200
	ds_read_b128 v[218:221], v184 offset:52224
	ds_read_b128 v[222:225], v184 offset:53248
	ds_read_b128 v[226:229], v184 offset:54272
	ds_read_b128 v[230:233], v184 offset:55296
	ds_read_b128 v[234:237], v184 offset:56320
	global_load_lds_dwordx4 v[164:165], off
	s_add_i32 m0, s46, 0x2000
	s_add_u32 s46, s60, 0x200080
	v_lshl_add_u64 v[164:165], v[242:243], 0, s[42:43]
	s_addc_u32 s47, s61, 0
	s_add_i32 s48, s49, s72
	global_load_lds_dwordx4 v[164:165], off
	v_lshl_add_u64 v[164:165], s[46:47], 0, v[166:167]
	s_mov_b32 m0, s48
	s_nop 0
	global_load_lds_dwordx4 v[164:165], off
	v_lshl_add_u64 v[164:165], s[46:47], 0, v[154:155]
	s_add_i32 m0, s48, 0x2000
	s_nop 0
	global_load_lds_dwordx4 v[164:165], off
	v_lshl_add_u64 v[164:165], v[244:245], 0, s[42:43]
	s_mov_b32 m0, s76
	s_nop 0
	global_load_lds_dwordx4 v[164:165], off
	v_lshl_add_u64 v[164:165], v[246:247], 0, s[42:43]
	s_mov_b32 m0, s77
	s_nop 0
	global_load_lds_dwordx4 v[164:165], off
	s_waitcnt vmcnt(8)
	s_waitcnt lgkmcnt(0)
	s_setprio 1
	s_waitcnt lgkmcnt(0)
	v_mfma_f32_16x16x32_bf16 v[62:65], v[130:133], v[206:209], v[62:65]
	v_mfma_f32_16x16x32_bf16 v[58:61], v[138:141], v[206:209], v[58:61]
	s_barrier
	v_mfma_f32_16x16x32_bf16 v[50:53], v[130:133], v[214:217], v[50:53]
	v_mfma_f32_16x16x32_bf16 v[42:45], v[138:141], v[214:217], v[42:45]
	v_mfma_f32_16x16x32_bf16 v[34:37], v[130:133], v[222:225], v[34:37]
	v_mfma_f32_16x16x32_bf16 v[26:29], v[138:141], v[222:225], v[26:29]
	v_mfma_f32_16x16x32_bf16 v[18:21], v[130:133], v[230:233], v[18:21]
	v_mfma_f32_16x16x32_bf16 v[10:13], v[138:141], v[230:233], v[10:13]
	v_mfma_f32_16x16x32_bf16 v[62:65], v[134:137], v[210:213], v[62:65]
	v_mfma_f32_16x16x32_bf16 v[58:61], v[142:145], v[210:213], v[58:61]
	v_mfma_f32_16x16x32_bf16 v[50:53], v[134:137], v[218:221], v[50:53]
	v_mfma_f32_16x16x32_bf16 v[42:45], v[142:145], v[218:221], v[42:45]
	v_mfma_f32_16x16x32_bf16 v[34:37], v[134:137], v[226:229], v[34:37]
	v_mfma_f32_16x16x32_bf16 v[26:29], v[142:145], v[226:229], v[26:29]
	v_mfma_f32_16x16x32_bf16 v[18:21], v[134:137], v[234:237], v[18:21]
	v_mfma_f32_16x16x32_bf16 v[10:13], v[142:145], v[234:237], v[10:13]
	v_mfma_f32_16x16x32_bf16 v[54:57], v[146:149], v[206:209], v[54:57]
	v_mfma_f32_16x16x32_bf16 v[46:49], v[178:181], v[206:209], v[46:49]
	v_mfma_f32_16x16x32_bf16 v[38:41], v[146:149], v[214:217], v[38:41]
	v_mfma_f32_16x16x32_bf16 v[30:33], v[178:181], v[214:217], v[30:33]
	v_mfma_f32_16x16x32_bf16 v[22:25], v[146:149], v[222:225], v[22:25]
	v_mfma_f32_16x16x32_bf16 v[14:17], v[178:181], v[222:225], v[14:17]
	v_mfma_f32_16x16x32_bf16 v[6:9], v[146:149], v[230:233], v[6:9]
	v_mfma_f32_16x16x32_bf16 v[2:5], v[178:181], v[230:233], v[2:5]
	v_mfma_f32_16x16x32_bf16 v[54:57], v[160:163], v[210:213], v[54:57]
	v_mfma_f32_16x16x32_bf16 v[46:49], v[186:189], v[210:213], v[46:49]
	v_mfma_f32_16x16x32_bf16 v[38:41], v[160:163], v[218:221], v[38:41]
	v_mfma_f32_16x16x32_bf16 v[30:33], v[186:189], v[218:221], v[30:33]
	v_mfma_f32_16x16x32_bf16 v[22:25], v[160:163], v[226:229], v[22:25]
	v_mfma_f32_16x16x32_bf16 v[14:17], v[186:189], v[226:229], v[14:17]
	v_mfma_f32_16x16x32_bf16 v[6:9], v[160:163], v[234:237], v[6:9]
	v_mfma_f32_16x16x32_bf16 v[2:5], v[186:189], v[234:237], v[2:5]
	s_barrier
	s_setprio 0
	s_add_i32 s84, s84, 2
	s_add_u32 s64, s64, 0x100
	s_addc_u32 s65, s65, 0
	s_add_u32 s82, s82, 0x100
	s_addc_u32 s83, s83, 0
	s_cmpk_gt_u32 s84, 0x7d
	s_cbranch_scc0 .LBB0_1112
	s_and_b64 vcc, exec, s[12:13]
	s_cbranch_vccz .LBB0_1115
	s_barrier

.LBB0_1138:
	s_add_u32 s46, s62, 0xffe00080
	s_addc_u32 s47, s63, -1
	s_add_i32 s48, 0, 0x10000
	s_cmpk_eq_i32 s82, 0x7c
	s_cselect_b32 s65, s17, s47
	s_cselect_b32 s64, s78, s46
	s_cselect_b32 s61, s13, s81
	s_cselect_b32 s60, s79, s80
	s_add_i32 s49, 0, 0x14000
	v_add_u32_e32 v142, s48, v186
	v_add_u32_e32 v164, s49, v186
	ds_read_b128 v[130:133], v142
	ds_read_b128 v[134:137], v142 offset:1024
	ds_read_b128 v[138:141], v142 offset:2048
	ds_read_b128 v[142:145], v142 offset:3072
	ds_read_b128 v[146:149], v164
	ds_read_b128 v[160:163], v164 offset:1024
	ds_read_b128 v[178:181], v164 offset:2048
	ds_read_b128 v[182:185], v164 offset:3072
	v_lshl_add_u64 v[164:165], s[62:63], 0, v[156:157]
	s_add_i32 m0, s71, 0xc000
	ds_read_b128 v[206:209], v188
	ds_read_b128 v[210:213], v188 offset:1024
	ds_read_b128 v[214:217], v188 offset:2048
	ds_read_b128 v[218:221], v188 offset:3072
	ds_read_b128 v[222:225], v188 offset:4096
	ds_read_b128 v[226:229], v188 offset:5120
	ds_read_b128 v[230:233], v188 offset:6144
	ds_read_b128 v[234:237], v188 offset:7168
	global_load_lds_dwordx4 v[164:165], off
	v_lshl_add_u64 v[164:165], s[62:63], 0, v[158:159]
	s_add_i32 m0, s71, 0xe000
	s_nop 0
	global_load_lds_dwordx4 v[164:165], off
	s_waitcnt vmcnt(8)
	s_waitcnt lgkmcnt(0)
	s_setprio 1
	s_waitcnt lgkmcnt(0)
	v_mfma_f32_16x16x32_bf16 v[126:129], v[130:133], v[206:209], v[126:129]
	v_mfma_f32_16x16x32_bf16 v[122:125], v[138:141], v[206:209], v[122:125]
	v_mfma_f32_16x16x32_bf16 v[118:121], v[130:133], v[214:217], v[118:121]
	v_mfma_f32_16x16x32_bf16 v[110:113], v[138:141], v[214:217], v[110:113]
	v_mfma_f32_16x16x32_bf16 v[94:97], v[130:133], v[222:225], v[94:97]
	v_mfma_f32_16x16x32_bf16 v[90:93], v[138:141], v[222:225], v[90:93]
	s_barrier
	v_mfma_f32_16x16x32_bf16 v[82:85], v[130:133], v[230:233], v[82:85]
	v_mfma_f32_16x16x32_bf16 v[74:77], v[138:141], v[230:233], v[74:77]
	v_mfma_f32_16x16x32_bf16 v[126:129], v[134:137], v[210:213], v[126:129]
	v_mfma_f32_16x16x32_bf16 v[122:125], v[142:145], v[210:213], v[122:125]
	v_mfma_f32_16x16x32_bf16 v[118:121], v[134:137], v[218:221], v[118:121]
	v_mfma_f32_16x16x32_bf16 v[110:113], v[142:145], v[218:221], v[110:113]
	v_mfma_f32_16x16x32_bf16 v[94:97], v[134:137], v[226:229], v[94:97]
	v_mfma_f32_16x16x32_bf16 v[90:93], v[142:145], v[226:229], v[90:93]
	v_mfma_f32_16x16x32_bf16 v[82:85], v[134:137], v[234:237], v[82:85]
	v_mfma_f32_16x16x32_bf16 v[74:77], v[142:145], v[234:237], v[74:77]
	v_mfma_f32_16x16x32_bf16 v[114:117], v[146:149], v[206:209], v[114:117]
	v_mfma_f32_16x16x32_bf16 v[106:109], v[178:181], v[206:209], v[106:109]
	v_mfma_f32_16x16x32_bf16 v[102:105], v[146:149], v[214:217], v[102:105]
	v_mfma_f32_16x16x32_bf16 v[98:101], v[178:181], v[214:217], v[98:101]
	v_mfma_f32_16x16x32_bf16 v[86:89], v[146:149], v[222:225], v[86:89]
	v_mfma_f32_16x16x32_bf16 v[78:81], v[178:181], v[222:225], v[78:81]
	v_mfma_f32_16x16x32_bf16 v[70:73], v[146:149], v[230:233], v[70:73]
	v_mfma_f32_16x16x32_bf16 v[66:69], v[178:181], v[230:233], v[66:69]
	v_mfma_f32_16x16x32_bf16 v[114:117], v[160:163], v[210:213], v[114:117]
	v_mfma_f32_16x16x32_bf16 v[106:109], v[182:185], v[210:213], v[106:109]
	v_mfma_f32_16x16x32_bf16 v[102:105], v[160:163], v[218:221], v[102:105]
	v_mfma_f32_16x16x32_bf16 v[98:101], v[182:185], v[218:221], v[98:101]
	v_mfma_f32_16x16x32_bf16 v[86:89], v[160:163], v[226:229], v[86:89]
	v_mfma_f32_16x16x32_bf16 v[78:81], v[182:185], v[226:229], v[78:81]
	v_mfma_f32_16x16x32_bf16 v[70:73], v[160:163], v[234:237], v[70:73]
	v_mfma_f32_16x16x32_bf16 v[66:69], v[182:185], v[234:237], v[66:69]
	s_barrier
	s_setprio 0
	s_add_i32 s46, s48, s70
	v_lshl_add_u64 v[164:165], s[60:61], 0, v[166:167]
	s_mov_b32 m0, s46
	ds_read_b128 v[206:209], v188 offset:16384
	ds_read_b128 v[210:213], v188 offset:17408
	ds_read_b128 v[214:217], v188 offset:18432
	ds_read_b128 v[218:221], v188 offset:19456
	ds_read_b128 v[222:225], v188 offset:20480
	ds_read_b128 v[226:229], v188 offset:21504
	ds_read_b128 v[230:233], v188 offset:22528
	ds_read_b128 v[234:237], v188 offset:23552
	global_load_lds_dwordx4 v[164:165], off
	s_add_i32 m0, s46, 0x2000
	s_add_u32 s46, s60, 0x200000
	v_lshl_add_u64 v[242:243], s[60:61], 0, v[154:155]
	s_addc_u32 s47, s61, 0
	s_add_i32 s48, s49, s70
	global_load_lds_dwordx4 v[242:243], off
	v_lshl_add_u64 v[244:245], s[46:47], 0, v[166:167]
	s_mov_b32 m0, s48
	v_lshl_add_u64 v[246:247], s[64:65], 0, v[152:153]
	global_load_lds_dwordx4 v[244:245], off
	v_lshl_add_u64 v[244:245], s[46:47], 0, v[154:155]
	s_add_i32 m0, s48, 0x2000
	s_nop 0
	global_load_lds_dwordx4 v[244:245], off
	v_lshl_add_u64 v[244:245], s[64:65], 0, v[150:151]
	s_mov_b32 m0, s71
	s_nop 0
	global_load_lds_dwordx4 v[244:245], off
	s_mov_b32 m0, s72
	s_nop 0
	global_load_lds_dwordx4 v[246:247], off
	s_waitcnt vmcnt(8)
	s_waitcnt lgkmcnt(0)
	s_setprio 1
	s_waitcnt lgkmcnt(0)
	v_mfma_f32_16x16x32_bf16 v[62:65], v[130:133], v[206:209], v[62:65]
	v_mfma_f32_16x16x32_bf16 v[58:61], v[138:141], v[206:209], v[58:61]
	s_barrier
	v_mfma_f32_16x16x32_bf16 v[50:53], v[130:133], v[214:217], v[50:53]
	v_mfma_f32_16x16x32_bf16 v[42:45], v[138:141], v[214:217], v[42:45]
	v_mfma_f32_16x16x32_bf16 v[34:37], v[130:133], v[222:225], v[34:37]
	v_mfma_f32_16x16x32_bf16 v[26:29], v[138:141], v[222:225], v[26:29]
	v_mfma_f32_16x16x32_bf16 v[18:21], v[130:133], v[230:233], v[18:21]
	v_mfma_f32_16x16x32_bf16 v[10:13], v[138:141], v[230:233], v[10:13]
	v_mfma_f32_16x16x32_bf16 v[62:65], v[134:137], v[210:213], v[62:65]
	v_mfma_f32_16x16x32_bf16 v[58:61], v[142:145], v[210:213], v[58:61]
	v_mfma_f32_16x16x32_bf16 v[50:53], v[134:137], v[218:221], v[50:53]
	v_mfma_f32_16x16x32_bf16 v[42:45], v[142:145], v[218:221], v[42:45]
	v_mfma_f32_16x16x32_bf16 v[34:37], v[134:137], v[226:229], v[34:37]
	v_mfma_f32_16x16x32_bf16 v[26:29], v[142:145], v[226:229], v[26:29]
	v_mfma_f32_16x16x32_bf16 v[18:21], v[134:137], v[234:237], v[18:21]
	v_mfma_f32_16x16x32_bf16 v[10:13], v[142:145], v[234:237], v[10:13]
	v_mfma_f32_16x16x32_bf16 v[54:57], v[146:149], v[206:209], v[54:57]
	v_mfma_f32_16x16x32_bf16 v[46:49], v[178:181], v[206:209], v[46:49]
	v_mfma_f32_16x16x32_bf16 v[38:41], v[146:149], v[214:217], v[38:41]
	v_mfma_f32_16x16x32_bf16 v[30:33], v[178:181], v[214:217], v[30:33]
	v_mfma_f32_16x16x32_bf16 v[22:25], v[146:149], v[222:225], v[22:25]
	v_mfma_f32_16x16x32_bf16 v[14:17], v[178:181], v[222:225], v[14:17]
	v_mfma_f32_16x16x32_bf16 v[6:9], v[146:149], v[230:233], v[6:9]
	v_mfma_f32_16x16x32_bf16 v[2:5], v[178:181], v[230:233], v[2:5]
	v_mfma_f32_16x16x32_bf16 v[54:57], v[160:163], v[210:213], v[54:57]
	v_mfma_f32_16x16x32_bf16 v[46:49], v[182:185], v[210:213], v[46:49]
	v_mfma_f32_16x16x32_bf16 v[38:41], v[160:163], v[218:221], v[38:41]
	v_mfma_f32_16x16x32_bf16 v[30:33], v[182:185], v[218:221], v[30:33]
	v_mfma_f32_16x16x32_bf16 v[22:25], v[160:163], v[226:229], v[22:25]
	v_mfma_f32_16x16x32_bf16 v[14:17], v[182:185], v[226:229], v[14:17]
	v_mfma_f32_16x16x32_bf16 v[6:9], v[160:163], v[234:237], v[6:9]
	v_mfma_f32_16x16x32_bf16 v[2:5], v[182:185], v[234:237], v[2:5]
	s_barrier
	s_setprio 0
	s_add_i32 s48, 0, 0x18000
	s_add_i32 s49, 0, 0x1c000
	v_add_u32_e32 v142, s48, v186
	v_add_u32_e32 v182, s49, v186
	ds_read_b128 v[130:133], v142
	ds_read_b128 v[134:137], v142 offset:1024
	ds_read_b128 v[138:141], v142 offset:2048
	ds_read_b128 v[142:145], v142 offset:3072
	ds_read_b128 v[146:149], v182
	ds_read_b128 v[160:163], v182 offset:1024
	ds_read_b128 v[178:181], v182 offset:2048
	ds_read_b128 v[182:185], v182 offset:3072
	s_add_u32 s46, s64, 0x200000
	s_addc_u32 s47, s65, 0
	s_mov_b32 m0, s73
	v_lshl_add_u64 v[248:249], s[46:47], 0, v[150:151]
	ds_read_b128 v[206:209], v188 offset:32768
	ds_read_b128 v[210:213], v188 offset:33792
	ds_read_b128 v[214:217], v188 offset:34816
	ds_read_b128 v[218:221], v188 offset:35840
	ds_read_b128 v[222:225], v188 offset:36864
	ds_read_b128 v[226:229], v188 offset:37888
	ds_read_b128 v[230:233], v188 offset:38912
	ds_read_b128 v[234:237], v188 offset:39936
	global_load_lds_dwordx4 v[248:249], off
	v_lshl_add_u64 v[248:249], s[46:47], 0, v[152:153]
	s_mov_b32 m0, s74
	s_nop 0
	global_load_lds_dwordx4 v[248:249], off
	s_waitcnt vmcnt(8)
	s_waitcnt lgkmcnt(0)
	s_setprio 1
	s_waitcnt lgkmcnt(0)
	v_mfma_f32_16x16x32_bf16 v[126:129], v[130:133], v[206:209], v[126:129]
	v_mfma_f32_16x16x32_bf16 v[122:125], v[138:141], v[206:209], v[122:125]
	v_mfma_f32_16x16x32_bf16 v[118:121], v[130:133], v[214:217], v[118:121]
	v_mfma_f32_16x16x32_bf16 v[110:113], v[138:141], v[214:217], v[110:113]
	v_mfma_f32_16x16x32_bf16 v[94:97], v[130:133], v[222:225], v[94:97]
	v_mfma_f32_16x16x32_bf16 v[90:93], v[138:141], v[222:225], v[90:93]
	s_barrier
	v_mfma_f32_16x16x32_bf16 v[82:85], v[130:133], v[230:233], v[82:85]
	v_mfma_f32_16x16x32_bf16 v[74:77], v[138:141], v[230:233], v[74:77]
	v_mfma_f32_16x16x32_bf16 v[126:129], v[134:137], v[210:213], v[126:129]
	v_mfma_f32_16x16x32_bf16 v[122:125], v[142:145], v[210:213], v[122:125]
	v_mfma_f32_16x16x32_bf16 v[118:121], v[134:137], v[218:221], v[118:121]
	v_mfma_f32_16x16x32_bf16 v[110:113], v[142:145], v[218:221], v[110:113]
	v_mfma_f32_16x16x32_bf16 v[94:97], v[134:137], v[226:229], v[94:97]
	v_mfma_f32_16x16x32_bf16 v[90:93], v[142:145], v[226:229], v[90:93]
	v_mfma_f32_16x16x32_bf16 v[82:85], v[134:137], v[234:237], v[82:85]
	v_mfma_f32_16x16x32_bf16 v[74:77], v[142:145], v[234:237], v[74:77]
	v_mfma_f32_16x16x32_bf16 v[114:117], v[146:149], v[206:209], v[114:117]
	v_mfma_f32_16x16x32_bf16 v[106:109], v[178:181], v[206:209], v[106:109]
	v_mfma_f32_16x16x32_bf16 v[102:105], v[146:149], v[214:217], v[102:105]
	v_mfma_f32_16x16x32_bf16 v[98:101], v[178:181], v[214:217], v[98:101]
	v_mfma_f32_16x16x32_bf16 v[86:89], v[146:149], v[222:225], v[86:89]
	v_mfma_f32_16x16x32_bf16 v[78:81], v[178:181], v[222:225], v[78:81]
	v_mfma_f32_16x16x32_bf16 v[70:73], v[146:149], v[230:233], v[70:73]
	v_mfma_f32_16x16x32_bf16 v[66:69], v[178:181], v[230:233], v[66:69]
	v_mfma_f32_16x16x32_bf16 v[114:117], v[160:163], v[210:213], v[114:117]
	v_mfma_f32_16x16x32_bf16 v[106:109], v[182:185], v[210:213], v[106:109]
	v_mfma_f32_16x16x32_bf16 v[102:105], v[160:163], v[218:221], v[102:105]
	v_mfma_f32_16x16x32_bf16 v[98:101], v[182:185], v[218:221], v[98:101]
	v_mfma_f32_16x16x32_bf16 v[86:89], v[160:163], v[226:229], v[86:89]
	v_mfma_f32_16x16x32_bf16 v[78:81], v[182:185], v[226:229], v[78:81]
	v_mfma_f32_16x16x32_bf16 v[70:73], v[160:163], v[234:237], v[70:73]
	v_mfma_f32_16x16x32_bf16 v[66:69], v[182:185], v[234:237], v[66:69]
	s_barrier
	s_setprio 0
	s_add_i32 s46, s48, s70
	v_lshl_add_u64 v[164:165], v[164:165], 0, s[42:43]
	s_mov_b32 m0, s46
	ds_read_b128 v[206:209], v188 offset:49152
	ds_read_b128 v[210:213], v188 offset:50176
	ds_read_b128 v[214:217], v188 offset:51200
	ds_read_b128 v[218:221], v188 offset:52224
	ds_read_b128 v[222:225], v188 offset:53248
	ds_read_b128 v[226:229], v188 offset:54272
	ds_read_b128 v[230:233], v188 offset:55296
	ds_read_b128 v[234:237], v188 offset:56320
	global_load_lds_dwordx4 v[164:165], off
	s_add_i32 m0, s46, 0x2000
	s_add_u32 s46, s60, 0x200080
	v_lshl_add_u64 v[164:165], v[242:243], 0, s[42:43]
	s_addc_u32 s47, s61, 0
	s_add_i32 s48, s49, s70
	global_load_lds_dwordx4 v[164:165], off
	v_lshl_add_u64 v[164:165], s[46:47], 0, v[166:167]
	s_mov_b32 m0, s48
	s_nop 0
	global_load_lds_dwordx4 v[164:165], off
	v_lshl_add_u64 v[164:165], s[46:47], 0, v[154:155]
	s_add_i32 m0, s48, 0x2000
	s_nop 0
	global_load_lds_dwordx4 v[164:165], off
	v_lshl_add_u64 v[164:165], v[244:245], 0, s[42:43]
	s_mov_b32 m0, s75
	s_nop 0
	global_load_lds_dwordx4 v[164:165], off
	v_lshl_add_u64 v[164:165], v[246:247], 0, s[42:43]
	s_mov_b32 m0, s76
	s_nop 0
	global_load_lds_dwordx4 v[164:165], off
	s_waitcnt vmcnt(8)
	s_waitcnt lgkmcnt(0)
	s_setprio 1
	s_waitcnt lgkmcnt(0)
	v_mfma_f32_16x16x32_bf16 v[62:65], v[130:133], v[206:209], v[62:65]
	v_mfma_f32_16x16x32_bf16 v[58:61], v[138:141], v[206:209], v[58:61]
	s_barrier
	v_mfma_f32_16x16x32_bf16 v[50:53], v[130:133], v[214:217], v[50:53]
	v_mfma_f32_16x16x32_bf16 v[42:45], v[138:141], v[214:217], v[42:45]
	v_mfma_f32_16x16x32_bf16 v[34:37], v[130:133], v[222:225], v[34:37]
	v_mfma_f32_16x16x32_bf16 v[26:29], v[138:141], v[222:225], v[26:29]
	v_mfma_f32_16x16x32_bf16 v[18:21], v[130:133], v[230:233], v[18:21]
	v_mfma_f32_16x16x32_bf16 v[10:13], v[138:141], v[230:233], v[10:13]
	v_mfma_f32_16x16x32_bf16 v[62:65], v[134:137], v[210:213], v[62:65]
	v_mfma_f32_16x16x32_bf16 v[58:61], v[142:145], v[210:213], v[58:61]
	v_mfma_f32_16x16x32_bf16 v[50:53], v[134:137], v[218:221], v[50:53]
	v_mfma_f32_16x16x32_bf16 v[42:45], v[142:145], v[218:221], v[42:45]
	v_mfma_f32_16x16x32_bf16 v[34:37], v[134:137], v[226:229], v[34:37]
	v_mfma_f32_16x16x32_bf16 v[26:29], v[142:145], v[226:229], v[26:29]
	v_mfma_f32_16x16x32_bf16 v[18:21], v[134:137], v[234:237], v[18:21]
	v_mfma_f32_16x16x32_bf16 v[10:13], v[142:145], v[234:237], v[10:13]
	v_mfma_f32_16x16x32_bf16 v[54:57], v[146:149], v[206:209], v[54:57]
	v_mfma_f32_16x16x32_bf16 v[46:49], v[178:181], v[206:209], v[46:49]
	v_mfma_f32_16x16x32_bf16 v[38:41], v[146:149], v[214:217], v[38:41]
	v_mfma_f32_16x16x32_bf16 v[30:33], v[178:181], v[214:217], v[30:33]
	v_mfma_f32_16x16x32_bf16 v[22:25], v[146:149], v[222:225], v[22:25]
	v_mfma_f32_16x16x32_bf16 v[14:17], v[178:181], v[222:225], v[14:17]
	v_mfma_f32_16x16x32_bf16 v[6:9], v[146:149], v[230:233], v[6:9]
	v_mfma_f32_16x16x32_bf16 v[2:5], v[178:181], v[230:233], v[2:5]
	v_mfma_f32_16x16x32_bf16 v[54:57], v[160:163], v[210:213], v[54:57]
	v_mfma_f32_16x16x32_bf16 v[46:49], v[182:185], v[210:213], v[46:49]
	v_mfma_f32_16x16x32_bf16 v[38:41], v[160:163], v[218:221], v[38:41]
	v_mfma_f32_16x16x32_bf16 v[30:33], v[182:185], v[218:221], v[30:33]
	v_mfma_f32_16x16x32_bf16 v[22:25], v[160:163], v[226:229], v[22:25]
	v_mfma_f32_16x16x32_bf16 v[14:17], v[182:185], v[226:229], v[14:17]
	v_mfma_f32_16x16x32_bf16 v[6:9], v[160:163], v[234:237], v[6:9]
	v_mfma_f32_16x16x32_bf16 v[2:5], v[182:185], v[234:237], v[2:5]
	s_barrier
	s_setprio 0
	s_add_i32 s82, s82, 2
	s_add_u32 s62, s62, 0x100
	s_addc_u32 s63, s63, 0
	s_add_u32 s80, s80, 0x100
	s_addc_u32 s81, s81, 0
	s_cmpk_gt_u32 s82, 0x7d
	s_cbranch_scc0 .LBB0_1138
	s_and_b64 vcc, exec, s[10:11]
	s_cbranch_vccz .LBB0_1141
	s_barrier
